# attention: redundant wait states between the score MFMAs and their first VALU reader trimmed
# speedup vs baseline: 1.0044x; 1.0044x over previous
; DI int otid() { int t = threadIdx.x & 255; asm volatile("" : "+v"(t)); return t; }
; template <int NKB>
; DI void attn_unit(const Params& p, int l, int mode, int grp, int head, int r0, int dil, int i0, int sub_len, int W, h16* lds) {
;     ...
;   h16* Qi = lds; h16* Ki = lds + 64 * LDH; h16* Vt = lds + 128 * LDH; h16* Pi = lds + 192 * LDH;
;   const int tid = otid(), lane = tid & 63, w = tid >> 6, r = lane & 15, q = lane >> 4;
;   const int lrow = tid >> 2, seg = tid & 3;
;   int qcol, kcol, vcol;
;   if (mode == 0) { qcol = 1024 + grp * 256 + head * 64; kcol = 1792 + grp * 256 + head * 64; vcol = 2560 + grp * 256 + head * 64; }
;   else { qcol = 4352 + head * 64; kcol = 4864 + (head >> 2) * 64; vcol = 4992 + (head >> 2) * 64; }
;   __syncthreads();
;   {
;     const size_t pos = (size_t)r0 + (size_t)dil * (i0 + lrow);
;     const h16* g = P + pos * NSM + qcol + 16 * seg;
;     img_store_nat(Qi, lrow, seg, *(const u4v*)g, *(const u4v*)(g + 8));
;   }
;   float mrow[4], lsum[4];
;   f4v O[4];
;   float m_init = -1e30f, l_init = 0.f;
;   if (mode == 1) { m_init = p.d_sink[l * 8 + head]; l_init = 1.f; }
; #pragma unroll
;   for (int i = 0; i < 4; ++i) { mrow[i] = m_init; lsum[i] = l_init; O[i] = (f4v){0.f, 0.f, 0.f, 0.f}; }
;   u4v pk0, pk1, pv0, pv1;
;     ...
;   ATT_PREFETCH(0);
; DI void phase_m2(const Params& p, int l, int bid, int nb, h16* lds) {
;     ...
;     v -= 2048;
;     const int grp = v >> 10, x = v & 1023, head = x & 3, tl = x >> 2;
;     const int dil = (grp == 0) ? 1 : (grp == 1) ? 4 : 16;
;     const int sub = SEQ / dil, tps = sub >> 6;
;     const int res = tl / tps, ti = tl % tps;
;     attn_unit<3>(p, l, 0, grp, head, res, dil, ti * 64, sub, 64, lds);
.LBB0_897:
	s_movk_i32 s2, 0x14a8
	v_cmp_gt_i32_e32 vcc, s2, v1
	s_and_saveexec_b64 s[2:3], vcc
	s_xor_b64 s[84:85], exec, s[2:3]
	s_cbranch_execz .LBB0_960
	v_cmp_lt_i32_e32 vcc, 31, v1
	s_and_saveexec_b64 s[2:3], vcc
	s_xor_b64 s[86:87], exec, s[2:3]
	s_cbranch_execz .LBB0_953
	s_movk_i32 s2, 0xa7
	v_cmp_lt_u32_e32 vcc, s2, v1
	s_and_saveexec_b64 s[2:3], vcc
	s_xor_b64 s[88:89], exec, s[2:3]
	s_cbranch_execz .LBB0_915
	s_movk_i32 s2, 0x8a7
	v_cmp_lt_u32_e32 vcc, s2, v1
	s_and_saveexec_b64 s[2:3], vcc
	s_xor_b64 s[34:35], exec, s[2:3]
	s_cbranch_execz .LBB0_910
	v_readfirstlane_b32 s36, v1
	v_readfirstlane_b32 s58, v182
	s_lshr_b32 s58, s58, 6
	s_sub_u32 s51, s36, 0x8a8
	s_and_b32 s56, s51, 15
	s_sub_u32 s56, s56, 8
	s_and_b32 s56, s56, 15
	s_lshr_b32 s56, s56, 1
	s_lshr_b32 s57, s51, 4
	s_lshl_b32 s57, s57, 1
	s_and_b32 s59, s51, 1
	s_or_b32 s57, s57, s59
	s_mul_i32 s59, s57, 0xaaab
	s_lshr_b32 s59, s59, 19
	s_mul_i32 s62, s59, 12
	s_sub_u32 s62, s57, s62
	s_lshr_b32 s61, s62, 2
	s_and_b32 s37, s62, 3
	s_lshl_b32 s62, s56, 5
	s_add_u32 s62, s62, s59
	s_lshl_b32 s63, s61, 1
	s_lshl_b32 s60, 1, s63
	s_movk_i32 s39, 0x2800
	s_lshl_b32 s39, s39, s63
	s_movk_i32 s41, 0x4000
	s_lshr_b32 s41, s41, s63
	s_sub_u32 s51, 8, s63
	s_lshr_b32 s40, s62, s51
	s_movk_i32 s51, 0x100
	s_lshr_b32 s51, s51, s63
	s_sub_u32 s51, s51, 1
	s_and_b32 s38, s62, s51
	s_lshl_b32 s38, s38, 6
	s_lshl_b32 s51, s61, 9
	s_lshl_b32 s56, s37, 7
	s_add_u32 s51, s51, s56
	s_add_u32 s53, s51, 0x800
	s_add_u32 s54, s51, 0xe00
	s_add_u32 s55, s51, 0x1400
	v_and_b32_e32 v179, 63, v182
	v_and_b32_e32 v200, 15, v179
	v_lshrrev_b32_e32 v201, 4, v179
	v_lshlrev_b32_e32 v202, 4, v201
	v_mad_u32_u24 v2, v200, s39, v202
	v_add_u32_e32 v203, 16, v200
	v_mad_u32_u24 v3, v203, s39, v202
	v_add_u32_e32 v203, 32, v200
	v_mad_u32_u24 v4, v203, s39, v202
	v_add_u32_e32 v203, 48, v200
	v_mad_u32_u24 v5, v203, s39, v202
	s_lshl_b32 s51, s58, 4
	v_add_u32_e32 v203, s51, v200
	v_mad_u32_u24 v248, v203, s39, v202
	v_lshlrev_b32_e32 v160, 2, v201
	v_sub_u32_e32 v160, v160, v203
	s_lshl_b32 s51, s60, 9
	v_mul_u32_u24_e32 v249, s51, v203
	s_lshl_b32 s51, s60, 5
	v_mul_u32_u24_e32 v203, s51, v203
	v_lshl_add_u32 v249, v201, 3, v249
	v_lshrrev_b32_e32 v203, 3, v179
	s_lshl_b32 s51, s58, 4
	v_add_u32_e32 v203, s51, v203
	v_and_b32_e32 v202, 7, v179
	v_lshlrev_b32_e32 v202, 4, v202
	v_mad_u32_u24 v6, v203, s39, v202
	v_add_u32_e32 v200, 8, v203
	v_mad_u32_u24 v7, v200, s39, v202
	s_movk_i32 s57, 0x90
	v_mad_u32_u24 v158, v203, s57, v183
	v_add_u32_e32 v158, v158, v202
	v_and_b32_e32 v200, 15, v179
	v_mad_u32_u24 v8, v200, s57, v183
	v_lshl_add_u32 v8, v201, 4, v8
	v_lshrrev_b32_e32 v203, 2, v179
	v_mad_u32_u24 v159, v203, s57, v183
	v_and_b32_e32 v203, 3, v179
	v_lshl_add_u32 v159, v203, 3, v159
	v_add_u32_e32 v159, 0x2400, v159
	v_xor_b32_e32 v174, 16, v179
	v_lshlrev_b32_e32 v174, 2, v174
	v_xor_b32_e32 v175, 32, v179
	v_lshlrev_b32_e32 v175, 2, v175
	s_mul_i32 s51, s60, s38
	s_add_u32 s51, s51, s40
	s_mul_i32 s56, s51, 0x2800
	s_add_u32 s56, s56, s53
	s_add_u32 s42, s0, s56
	s_addc_u32 s43, s1, 0
	global_load_dwordx4 v[10:13], v248, s[42:43]
	global_load_dwordx4 v[14:17], v248, s[42:43] offset:64
	v_readlane_b32 s48, v254, 32
	v_readlane_b32 s49, v254, 33
	v_readlane_b32 s16, v254, 34
	v_readlane_b32 s17, v254, 35
	s_lshl_b32 s56, s61, 14
	s_add_u32 s56, s56, s51
	s_lshl_b32 s57, s56, 9
	s_lshl_b32 s59, s37, 7
	s_add_u32 s57, s57, s59
	s_add_u32 s48, s48, s57
	s_addc_u32 s49, s49, 0
	s_lshl_b32 s57, s56, 5
	s_lshl_b32 s59, s37, 3
	s_add_u32 s57, s57, s59
	s_add_u32 s16, s16, s57
	s_addc_u32 s17, s17, 0
	v_mov_b32_e32 v176, 0xf149f2ca
	v_mov_b32_e32 v177, 0
	v_mov_b32_e32 v138, 0
	v_mov_b32_e32 v139, 0
	v_mov_b32_e32 v140, 0
	v_mov_b32_e32 v141, 0
	v_mov_b32_e32 v142, 0
	v_mov_b32_e32 v143, 0
	v_mov_b32_e32 v144, 0
	v_mov_b32_e32 v145, 0
	v_mov_b32_e32 v146, 0
	v_mov_b32_e32 v147, 0
	v_mov_b32_e32 v148, 0
	v_mov_b32_e32 v149, 0
	v_mov_b32_e32 v150, 0
	v_mov_b32_e32 v151, 0
	v_mov_b32_e32 v152, 0
	v_mov_b32_e32 v153, 0
	s_sub_u32 s50, s38, 64
	s_cmp_ge_i32 s50, 0
	s_cselect_b32 s56, 1, 0
	s_cmp_lt_i32 s50, s41
	s_cselect_b32 s57, 1, 0
	s_and_b32 s2, s56, s57
	s_cmp_eq_u32 s2, 1
	s_cselect_b32 s50, s50, s38
	s_mul_i32 s50, s50, s60
	s_add_u32 s50, s50, s40
	s_mul_i32 s50, s50, 0x2800
	s_add_u32 s56, s50, s54
	s_add_u32 s44, s0, s56
	s_addc_u32 s45, s1, 0
	s_add_u32 s56, s50, s55
	s_add_u32 s46, s0, s56
	s_addc_u32 s47, s1, 0
	global_load_dwordx4 v[50:53], v6, s[44:45]
	global_load_dwordx4 v[54:57], v7, s[44:45]
	global_load_dwordx4 v[58:61], v6, s[46:47]
	global_load_dwordx4 v[62:65], v7, s[46:47]
	s_add_u32 s50, s38, 0
	s_cmp_ge_i32 s50, 0
	s_cselect_b32 s56, 1, 0
	s_cmp_lt_i32 s50, s41
	s_cselect_b32 s57, 1, 0
	s_and_b32 s3, s56, s57
	s_cmp_eq_u32 s3, 1
	s_cselect_b32 s50, s50, s38
	s_mul_i32 s50, s50, s60
	s_add_u32 s50, s50, s40
	s_mul_i32 s50, s50, 0x2800
	s_add_u32 s56, s50, s54
	s_add_u32 s44, s0, s56
	s_addc_u32 s45, s1, 0
	s_add_u32 s56, s50, s55
	s_add_u32 s46, s0, s56
	s_addc_u32 s47, s1, 0
	global_load_dwordx4 v[66:69], v6, s[44:45]
	global_load_dwordx4 v[70:73], v7, s[44:45]
	global_load_dwordx4 v[74:77], v6, s[46:47]
	global_load_dwordx4 v[78:81], v7, s[46:47]
	s_waitcnt vmcnt(4)
	ds_write_b128 v158, v[50:53] offset:0
	ds_write_b128 v158, v[54:57] offset:1152
	ds_write_b128 v158, v[58:61] offset:9216
	ds_write_b128 v158, v[62:65] offset:10368
	s_waitcnt lgkmcnt(0)
	s_barrier
; DI float grp16_max(float v) { v = fmaxf(v, __shfl_xor(v, 1)); v = fmaxf(v, __shfl_xor(v, 2)); v = fmaxf(v, __shfl_xor(v, 4)); v = fmaxf(v, __shfl_xor(v, 8)); return v; }
; template <int NKB>
; DI void attn_unit(const Params& p, int l, int mode, int grp, int head, int r0, int dil, int i0, int sub_len, int W, h16* lds) {
;     ...
;   for (int kb = 0; kb < NKB; ++kb) {
;     const int j0 = i0 - W + 64 * kb;
;     const bool inr = (j0 >= 0) && (j0 < sub_len);
;     __syncthreads();
;     img_store_nat(Ki, lrow, seg, pk0, pk1);
;     img_store_T(Vt, lrow, seg, pv0, pv1);
;     __syncthreads();
;     if (kb + 1 < NKB) ATT_PREFETCH(kb + 1);
;     f4v S[4];
; #pragma unroll
;     for (int i = 0; i < 4; ++i) S[i] = (f4v){0.f, 0.f, 0.f, 0.f};
;     mm64(Qi, Ki, S, w, lane);
;     float mx[4], al[4], rsum[4];
;     bool vm[4][4];
; #pragma unroll
;     for (int rg = 0; rg < 4; ++rg) {
;       const int row = 16 * w + 4 * q + rg;
;       float m_ = -1e30f;
; #pragma unroll
;       for (int nt = 0; nt < 4; ++nt) {
;         const int key = 16 * nt + r;
;         const int delta = row - key + W - 64 * kb;
;         const bool ok = inr && (delta >= -W) && (delta <= W);
;         vm[nt][rg] = ok;
;         float s = S[nt][rg] * 0.125f;
;         S[nt][rg] = s;
;         if (ok) m_ = fmaxf(m_, s);
;       }
;       mx[rg] = grp16_max(m_);
;     }
; #pragma unroll
;     for (int rg = 0; rg < 4; ++rg) {
;       const float mn = fmaxf(mrow[rg], mx[rg]);
;       al[rg] = __expf(mrow[rg] - mn);
	s_add_u32 s50, s38, 64
	s_cmp_ge_i32 s50, 0
	s_cselect_b32 s56, 1, 0
	s_cmp_lt_i32 s50, s41
	s_cselect_b32 s57, 1, 0
	s_and_b32 s4, s56, s57
	s_cmp_eq_u32 s4, 1
	s_cselect_b32 s50, s50, s38
	s_mul_i32 s50, s50, s60
	s_add_u32 s50, s50, s40
	s_mul_i32 s50, s50, 0x2800
	s_add_u32 s56, s50, s54
	s_add_u32 s44, s0, s56
	s_addc_u32 s45, s1, 0
	s_add_u32 s56, s50, s55
	s_add_u32 s46, s0, s56
	s_addc_u32 s47, s1, 0
	global_load_dwordx4 v[50:53], v6, s[44:45]
	global_load_dwordx4 v[54:57], v7, s[44:45]
	global_load_dwordx4 v[58:61], v6, s[46:47]
	global_load_dwordx4 v[62:65], v7, s[46:47]
	s_cmp_eq_u32 s2, 1
	s_cbranch_scc0 .Lat0_kb0_end
	ds_read_b128 v[18:21], v8 offset:0
	ds_read_b128 v[22:25], v8 offset:64
	ds_read_b128 v[26:29], v8 offset:2304
	ds_read_b128 v[30:33], v8 offset:2368
	ds_read_b128 v[34:37], v8 offset:4608
	ds_read_b128 v[38:41], v8 offset:4672
	ds_read_b128 v[42:45], v8 offset:6912
	ds_read_b128 v[46:49], v8 offset:6976
	ds_read_b64_tr_b16 v[216:217], v159
	ds_read_b64_tr_b16 v[218:219], v159 offset:2304
	ds_read_b64_tr_b16 v[220:221], v159 offset:4608
	ds_read_b64_tr_b16 v[222:223], v159 offset:6912
	ds_read_b64_tr_b16 v[224:225], v159 offset:32
	ds_read_b64_tr_b16 v[226:227], v159 offset:2336
	ds_read_b64_tr_b16 v[228:229], v159 offset:4640
	ds_read_b64_tr_b16 v[230:231], v159 offset:6944
	ds_read_b64_tr_b16 v[232:233], v159 offset:64
	ds_read_b64_tr_b16 v[234:235], v159 offset:2368
	ds_read_b64_tr_b16 v[236:237], v159 offset:4672
	ds_read_b64_tr_b16 v[238:239], v159 offset:6976
	ds_read_b64_tr_b16 v[240:241], v159 offset:96
	ds_read_b64_tr_b16 v[242:243], v159 offset:2400
	ds_read_b64_tr_b16 v[244:245], v159 offset:4704
	ds_read_b64_tr_b16 v[246:247], v159 offset:7008
	s_waitcnt lgkmcnt(15)
	v_mfma_f32_16x16x32_f16 v[114:117], v[18:21], v[10:13], 0
	v_mfma_f32_16x16x32_f16 v[118:121], v[26:29], v[10:13], 0
	v_mfma_f32_16x16x32_f16 v[122:125], v[34:37], v[10:13], 0
	v_mfma_f32_16x16x32_f16 v[126:129], v[42:45], v[10:13], 0
	v_mfma_f32_16x16x32_f16 v[114:117], v[22:25], v[14:17], v[114:117]
	v_mfma_f32_16x16x32_f16 v[118:121], v[30:33], v[14:17], v[118:121]
	v_mfma_f32_16x16x32_f16 v[122:125], v[38:41], v[14:17], v[122:125]
	v_mfma_f32_16x16x32_f16 v[126:129], v[46:49], v[14:17], v[126:129]
	s_nop 7
	v_mul_f32_e32 v114, 0x3e000000, v114
	v_mul_f32_e32 v115, 0x3e000000, v115
	v_mul_f32_e32 v116, 0x3e000000, v116
	v_mul_f32_e32 v117, 0x3e000000, v117
	v_mul_f32_e32 v118, 0x3e000000, v118
	v_mul_f32_e32 v119, 0x3e000000, v119
	v_mul_f32_e32 v120, 0x3e000000, v120
	v_mul_f32_e32 v121, 0x3e000000, v121
	v_mul_f32_e32 v122, 0x3e000000, v122
	v_mul_f32_e32 v123, 0x3e000000, v123
	v_mul_f32_e32 v124, 0x3e000000, v124
	v_mul_f32_e32 v125, 0x3e000000, v125
	v_mul_f32_e32 v126, 0x3e000000, v126
	v_mul_f32_e32 v127, 0x3e000000, v127
	v_mul_f32_e32 v128, 0x3e000000, v128
	v_mul_f32_e32 v129, 0x3e000000, v129
	v_mov_b32_e32 v200, 0xf149f2ca
	v_cmp_le_i32_e32 vcc, 0, v160
	v_cndmask_b32_e32 v114, v200, v114, vcc
	v_cmp_le_i32_e32 vcc, -1, v160
	v_cndmask_b32_e32 v115, v200, v115, vcc
	v_cmp_le_i32_e32 vcc, -2, v160
	v_cndmask_b32_e32 v116, v200, v116, vcc
	v_cmp_le_i32_e32 vcc, -3, v160
	v_cndmask_b32_e32 v117, v200, v117, vcc
	v_cmp_le_i32_e32 vcc, -16, v160
	v_cndmask_b32_e32 v118, v200, v118, vcc
	v_cmp_le_i32_e32 vcc, -17, v160
	v_cndmask_b32_e32 v119, v200, v119, vcc
	v_cmp_le_i32_e32 vcc, -18, v160
	v_cndmask_b32_e32 v120, v200, v120, vcc
	v_cmp_le_i32_e32 vcc, -19, v160
	v_cndmask_b32_e32 v121, v200, v121, vcc
	v_cmp_le_i32_e32 vcc, -32, v160
	v_cndmask_b32_e32 v122, v200, v122, vcc
	v_cmp_le_i32_e32 vcc, -33, v160
	v_cndmask_b32_e32 v123, v200, v123, vcc
	v_cmp_le_i32_e32 vcc, -34, v160
	v_cndmask_b32_e32 v124, v200, v124, vcc
	v_cmp_le_i32_e32 vcc, -35, v160
	v_cndmask_b32_e32 v125, v200, v125, vcc
	v_cmp_le_i32_e32 vcc, -48, v160
	v_cndmask_b32_e32 v126, v200, v126, vcc
	v_cmp_le_i32_e32 vcc, -49, v160
	v_cndmask_b32_e32 v127, v200, v127, vcc
	v_cmp_le_i32_e32 vcc, -50, v160
	v_cndmask_b32_e32 v128, v200, v128, vcc
	v_cmp_le_i32_e32 vcc, -51, v160
	v_cndmask_b32_e32 v129, v200, v129, vcc
	v_max3_f32 v179, v114, v115, v116
	v_max3_f32 v179, v179, v117, v118
	v_max3_f32 v179, v179, v119, v120
	v_max3_f32 v179, v179, v121, v122
	v_max3_f32 v179, v179, v123, v124
	v_max3_f32 v179, v179, v125, v126
	v_max3_f32 v179, v179, v127, v128
	v_max_f32_e32 v179, v179, v129
	ds_bpermute_b32 v201, v174, v179
	s_waitcnt lgkmcnt(0)
; DI float grp16_sum(float v) { v += __shfl_xor(v, 1); v += __shfl_xor(v, 2); v += __shfl_xor(v, 4); v += __shfl_xor(v, 8); return v; }
; DI float grp16_max(float v) { v = fmaxf(v, __shfl_xor(v, 1)); v = fmaxf(v, __shfl_xor(v, 2)); v = fmaxf(v, __shfl_xor(v, 4)); v = fmaxf(v, __shfl_xor(v, 8)); return v; }
; template <int NKB>
; DI void attn_unit(const Params& p, int l, int mode, int grp, int head, int r0, int dil, int i0, int sub_len, int W, h16* lds) {
;     ...
;   for (int kb = 0; kb < NKB; ++kb) {
;     const int j0 = i0 - W + 64 * kb;
;     const bool inr = (j0 >= 0) && (j0 < sub_len);
;     __syncthreads();
;     img_store_nat(Ki, lrow, seg, pk0, pk1);
;     img_store_T(Vt, lrow, seg, pv0, pv1);
;     __syncthreads();
;     if (kb + 1 < NKB) ATT_PREFETCH(kb + 1);
;     f4v S[4];
; #pragma unroll
;     for (int i = 0; i < 4; ++i) S[i] = (f4v){0.f, 0.f, 0.f, 0.f};
;     mm64(Qi, Ki, S, w, lane);
;     float mx[4], al[4], rsum[4];
;     bool vm[4][4];
; #pragma unroll
;     for (int rg = 0; rg < 4; ++rg) {
;       const int row = 16 * w + 4 * q + rg;
;       float m_ = -1e30f;
; #pragma unroll
;       for (int nt = 0; nt < 4; ++nt) {
;         const int key = 16 * nt + r;
;         const int delta = row - key + W - 64 * kb;
;         const bool ok = inr && (delta >= -W) && (delta <= W);
;         vm[nt][rg] = ok;
;         float s = S[nt][rg] * 0.125f;
;         S[nt][rg] = s;
;         if (ok) m_ = fmaxf(m_, s);
;       }
;       mx[rg] = grp16_max(m_);
;     }
; #pragma unroll
;     for (int rg = 0; rg < 4; ++rg) {
;       const float mn = fmaxf(mrow[rg], mx[rg]);
;       al[rg] = __expf(mrow[rg] - mn);
;       mrow[rg] = mn;
;       float rs_ = 0.f;
; #pragma unroll
;       for (int nt = 0; nt < 4; ++nt) {
;         float pv = vm[nt][rg] ? __expf(S[nt][rg] - mn) : 0.f;
;         rs_ += pv;
;         Pi[(16 * w + 4 * q + rg) * LDH + 16 * nt + r] = (h16)pv;
;       }
;       rsum[rg] = grp16_sum(rs_);
;       lsum[rg] = lsum[rg] * al[rg] + rsum[rg];
;     }
; #pragma unroll
;     for (int et = 0; et < 4; ++et)
; #pragma unroll
;       for (int rg = 0; rg < 4; ++rg) O[et][rg] *= al[rg];
;     __syncthreads();
;     mm64(Pi, Vt, O, w, lane);
;   }
	v_max_f32_e32 v179, v179, v201
	v_mov_b32_e32 v201, v179
	s_nop 1
	v_permlane32_swap_b32 v201, v179
	s_nop 1
	v_max3_f32 v179, v179, v201, v176
	v_sub_f32_e32 v178, v176, v179
	v_mul_f32_e32 v178, 0x3fb8aa3b, v178
	v_exp_f32_e32 v178, v178
	v_mov_b32_e32 v176, v179
	v_mul_f32_e32 v202, 0xbfb8aa3b, v179
	v_mov_b32_e32 v203, 0x3fb8aa3b
	v_fma_f32 v114, v114, v203, v202
	v_fma_f32 v115, v115, v203, v202
	v_fma_f32 v116, v116, v203, v202
	v_fma_f32 v117, v117, v203, v202
	v_fma_f32 v118, v118, v203, v202
	v_fma_f32 v119, v119, v203, v202
	v_fma_f32 v120, v120, v203, v202
	v_fma_f32 v121, v121, v203, v202
	v_fma_f32 v122, v122, v203, v202
	v_fma_f32 v123, v123, v203, v202
	v_fma_f32 v124, v124, v203, v202
	v_fma_f32 v125, v125, v203, v202
	v_fma_f32 v126, v126, v203, v202
	v_fma_f32 v127, v127, v203, v202
	v_fma_f32 v128, v128, v203, v202
	v_fma_f32 v129, v129, v203, v202
	v_exp_f32_e32 v114, v114
	v_exp_f32_e32 v115, v115
	v_exp_f32_e32 v116, v116
	v_exp_f32_e32 v117, v117
	v_exp_f32_e32 v118, v118
	v_exp_f32_e32 v119, v119
	v_exp_f32_e32 v120, v120
	v_exp_f32_e32 v121, v121
	v_exp_f32_e32 v122, v122
	v_exp_f32_e32 v123, v123
	v_exp_f32_e32 v124, v124
	v_exp_f32_e32 v125, v125
	v_exp_f32_e32 v126, v126
	v_exp_f32_e32 v127, v127
	v_exp_f32_e32 v128, v128
	v_exp_f32_e32 v129, v129
	s_nop 0
	v_fma_f32 v177, v177, v178, v114
	v_add_f32_e32 v177, v177, v115
	v_add_f32_e32 v177, v177, v116
	v_add_f32_e32 v177, v177, v117
	v_add_f32_e32 v177, v177, v118
	v_add_f32_e32 v177, v177, v119
	v_add_f32_e32 v177, v177, v120
	v_add_f32_e32 v177, v177, v121
	v_add_f32_e32 v177, v177, v122
	v_add_f32_e32 v177, v177, v123
	v_add_f32_e32 v177, v177, v124
	v_add_f32_e32 v177, v177, v125
	v_add_f32_e32 v177, v177, v126
	v_add_f32_e32 v177, v177, v127
	v_add_f32_e32 v177, v177, v128
	v_add_f32_e32 v177, v177, v129
	v_cvt_pk_f16_f32 v130, v114, v115
	v_cvt_pk_f16_f32 v131, v116, v117
	v_cvt_pk_f16_f32 v132, v118, v119
	v_cvt_pk_f16_f32 v133, v120, v121
	v_cvt_pk_f16_f32 v134, v122, v123
	v_cvt_pk_f16_f32 v135, v124, v125
	v_cvt_pk_f16_f32 v136, v126, v127
	v_cvt_pk_f16_f32 v137, v128, v129
	v_pk_mul_f32 v[138:139], v[138:139], v[178:179] op_sel_hi:[1,0]
	v_pk_mul_f32 v[140:141], v[140:141], v[178:179] op_sel_hi:[1,0]
	v_pk_mul_f32 v[142:143], v[142:143], v[178:179] op_sel_hi:[1,0]
	v_pk_mul_f32 v[144:145], v[144:145], v[178:179] op_sel_hi:[1,0]
	v_pk_mul_f32 v[146:147], v[146:147], v[178:179] op_sel_hi:[1,0]
	v_pk_mul_f32 v[148:149], v[148:149], v[178:179] op_sel_hi:[1,0]
	v_pk_mul_f32 v[150:151], v[150:151], v[178:179] op_sel_hi:[1,0]
	v_pk_mul_f32 v[152:153], v[152:153], v[178:179] op_sel_hi:[1,0]
	s_nop 1
	v_mfma_f32_16x16x32_f16 v[138:141], v[216:219], v[130:133], v[138:141]
	v_mfma_f32_16x16x32_f16 v[142:145], v[224:227], v[130:133], v[142:145]
	v_mfma_f32_16x16x32_f16 v[146:149], v[232:235], v[130:133], v[146:149]
	v_mfma_f32_16x16x32_f16 v[150:153], v[240:243], v[130:133], v[150:153]
	v_mfma_f32_16x16x32_f16 v[138:141], v[220:223], v[134:137], v[138:141]
	v_mfma_f32_16x16x32_f16 v[142:145], v[228:231], v[134:137], v[142:145]
	v_mfma_f32_16x16x32_f16 v[146:149], v[236:239], v[134:137], v[146:149]
	v_mfma_f32_16x16x32_f16 v[150:153], v[244:247], v[134:137], v[150:153]
.Lat0_kb0_end:
	s_waitcnt vmcnt(4)
	ds_write_b128 v158, v[66:69] offset:18432
	ds_write_b128 v158, v[70:73] offset:19584
	ds_write_b128 v158, v[74:77] offset:27648
	ds_write_b128 v158, v[78:81] offset:28800
	s_waitcnt lgkmcnt(0)
	s_barrier
	s_cmp_eq_u32 s3, 1
	s_cbranch_scc0 .Lat0_kb1_end
	ds_read_b128 v[18:21], v8 offset:18432
	ds_read_b128 v[22:25], v8 offset:18496
	ds_read_b128 v[26:29], v8 offset:20736
	ds_read_b128 v[30:33], v8 offset:20800
	ds_read_b128 v[34:37], v8 offset:23040
	ds_read_b128 v[38:41], v8 offset:23104
	ds_read_b128 v[42:45], v8 offset:25344
	ds_read_b128 v[46:49], v8 offset:25408
	ds_read_b64_tr_b16 v[216:217], v159 offset:18432
	ds_read_b64_tr_b16 v[218:219], v159 offset:20736
	ds_read_b64_tr_b16 v[220:221], v159 offset:23040
	ds_read_b64_tr_b16 v[222:223], v159 offset:25344
	ds_read_b64_tr_b16 v[224:225], v159 offset:18464
	ds_read_b64_tr_b16 v[226:227], v159 offset:20768
	ds_read_b64_tr_b16 v[228:229], v159 offset:23072
	ds_read_b64_tr_b16 v[230:231], v159 offset:25376
	ds_read_b64_tr_b16 v[232:233], v159 offset:18496
	ds_read_b64_tr_b16 v[234:235], v159 offset:20800
	ds_read_b64_tr_b16 v[236:237], v159 offset:23104
	ds_read_b64_tr_b16 v[238:239], v159 offset:25408
	ds_read_b64_tr_b16 v[240:241], v159 offset:18528
	ds_read_b64_tr_b16 v[242:243], v159 offset:20832
	ds_read_b64_tr_b16 v[244:245], v159 offset:23136
	ds_read_b64_tr_b16 v[246:247], v159 offset:25440
	s_waitcnt lgkmcnt(15)
	v_mfma_f32_16x16x32_f16 v[114:117], v[18:21], v[10:13], 0
	v_mfma_f32_16x16x32_f16 v[118:121], v[26:29], v[10:13], 0
	v_mfma_f32_16x16x32_f16 v[122:125], v[34:37], v[10:13], 0
	v_mfma_f32_16x16x32_f16 v[126:129], v[42:45], v[10:13], 0
	v_mfma_f32_16x16x32_f16 v[114:117], v[22:25], v[14:17], v[114:117]
	v_mfma_f32_16x16x32_f16 v[118:121], v[30:33], v[14:17], v[118:121]
	v_mfma_f32_16x16x32_f16 v[122:125], v[38:41], v[14:17], v[122:125]
	v_mfma_f32_16x16x32_f16 v[126:129], v[46:49], v[14:17], v[126:129]
	s_nop 7
	v_mul_f32_e32 v114, 0x3e000000, v114
	v_mul_f32_e32 v115, 0x3e000000, v115
	v_mul_f32_e32 v116, 0x3e000000, v116
	v_mul_f32_e32 v117, 0x3e000000, v117
	v_mul_f32_e32 v118, 0x3e000000, v118
	v_mul_f32_e32 v119, 0x3e000000, v119
	v_mul_f32_e32 v120, 0x3e000000, v120
	v_mul_f32_e32 v121, 0x3e000000, v121
	v_mul_f32_e32 v122, 0x3e000000, v122
	v_mul_f32_e32 v123, 0x3e000000, v123
	v_mul_f32_e32 v124, 0x3e000000, v124
	v_mul_f32_e32 v125, 0x3e000000, v125
	v_mul_f32_e32 v126, 0x3e000000, v126
	v_mul_f32_e32 v127, 0x3e000000, v127
	v_mul_f32_e32 v128, 0x3e000000, v128
	v_mul_f32_e32 v129, 0x3e000000, v129
	v_max3_f32 v179, v114, v115, v116
	v_max3_f32 v179, v179, v117, v118
	v_max3_f32 v179, v179, v119, v120
	v_max3_f32 v179, v179, v121, v122
	v_max3_f32 v179, v179, v123, v124
	v_max3_f32 v179, v179, v125, v126
	v_max3_f32 v179, v179, v127, v128
	v_max_f32_e32 v179, v179, v129
	ds_bpermute_b32 v201, v174, v179
	s_waitcnt lgkmcnt(0)
; DI float grp16_sum(float v) { v += __shfl_xor(v, 1); v += __shfl_xor(v, 2); v += __shfl_xor(v, 4); v += __shfl_xor(v, 8); return v; }
; template <int NKB>
; DI void attn_unit(const Params& p, int l, int mode, int grp, int head, int r0, int dil, int i0, int sub_len, int W, h16* lds) {
;     ...
;     for (int rg = 0; rg < 4; ++rg) {
;       const float mn = fmaxf(mrow[rg], mx[rg]);
;       al[rg] = __expf(mrow[rg] - mn);
;       mrow[rg] = mn;
;       float rs_ = 0.f;
; #pragma unroll
;       for (int nt = 0; nt < 4; ++nt) {
;         float pv = vm[nt][rg] ? __expf(S[nt][rg] - mn) : 0.f;
;         rs_ += pv;
;         Pi[(16 * w + 4 * q + rg) * LDH + 16 * nt + r] = (h16)pv;
;       }
;       rsum[rg] = grp16_sum(rs_);
;       lsum[rg] = lsum[rg] * al[rg] + rsum[rg];
;     }
; #pragma unroll
;     for (int et = 0; et < 4; ++et)
; #pragma unroll
;       for (int rg = 0; rg < 4; ++rg) O[et][rg] *= al[rg];
;     __syncthreads();
;     mm64(Pi, Vt, O, w, lane);
;   }
	v_max_f32_e32 v179, v179, v201
	v_mov_b32_e32 v201, v179
	s_nop 1
	v_permlane32_swap_b32 v201, v179
	s_nop 1
	v_max3_f32 v179, v179, v201, v176
	v_sub_f32_e32 v178, v176, v179
	v_mul_f32_e32 v178, 0x3fb8aa3b, v178
	v_exp_f32_e32 v178, v178
	v_mov_b32_e32 v176, v179
	v_mul_f32_e32 v202, 0xbfb8aa3b, v179
	v_mov_b32_e32 v203, 0x3fb8aa3b
	v_fma_f32 v114, v114, v203, v202
	v_fma_f32 v115, v115, v203, v202
	v_fma_f32 v116, v116, v203, v202
	v_fma_f32 v117, v117, v203, v202
	v_fma_f32 v118, v118, v203, v202
	v_fma_f32 v119, v119, v203, v202
	v_fma_f32 v120, v120, v203, v202
	v_fma_f32 v121, v121, v203, v202
	v_fma_f32 v122, v122, v203, v202
	v_fma_f32 v123, v123, v203, v202
	v_fma_f32 v124, v124, v203, v202
	v_fma_f32 v125, v125, v203, v202
	v_fma_f32 v126, v126, v203, v202
	v_fma_f32 v127, v127, v203, v202
	v_fma_f32 v128, v128, v203, v202
	v_fma_f32 v129, v129, v203, v202
	v_exp_f32_e32 v114, v114
	v_exp_f32_e32 v115, v115
	v_exp_f32_e32 v116, v116
	v_exp_f32_e32 v117, v117
	v_exp_f32_e32 v118, v118
	v_exp_f32_e32 v119, v119
	v_exp_f32_e32 v120, v120
	v_exp_f32_e32 v121, v121
	v_exp_f32_e32 v122, v122
	v_exp_f32_e32 v123, v123
	v_exp_f32_e32 v124, v124
	v_exp_f32_e32 v125, v125
	v_exp_f32_e32 v126, v126
	v_exp_f32_e32 v127, v127
	v_exp_f32_e32 v128, v128
	v_exp_f32_e32 v129, v129
	s_nop 0
	v_fma_f32 v177, v177, v178, v114
	v_add_f32_e32 v177, v177, v115
	v_add_f32_e32 v177, v177, v116
	v_add_f32_e32 v177, v177, v117
	v_add_f32_e32 v177, v177, v118
	v_add_f32_e32 v177, v177, v119
	v_add_f32_e32 v177, v177, v120
	v_add_f32_e32 v177, v177, v121
	v_add_f32_e32 v177, v177, v122
	v_add_f32_e32 v177, v177, v123
	v_add_f32_e32 v177, v177, v124
	v_add_f32_e32 v177, v177, v125
	v_add_f32_e32 v177, v177, v126
	v_add_f32_e32 v177, v177, v127
	v_add_f32_e32 v177, v177, v128
	v_add_f32_e32 v177, v177, v129
	v_cvt_pk_f16_f32 v130, v114, v115
	v_cvt_pk_f16_f32 v131, v116, v117
	v_cvt_pk_f16_f32 v132, v118, v119
	v_cvt_pk_f16_f32 v133, v120, v121
	v_cvt_pk_f16_f32 v134, v122, v123
	v_cvt_pk_f16_f32 v135, v124, v125
	v_cvt_pk_f16_f32 v136, v126, v127
	v_cvt_pk_f16_f32 v137, v128, v129
	v_pk_mul_f32 v[138:139], v[138:139], v[178:179] op_sel_hi:[1,0]
	v_pk_mul_f32 v[140:141], v[140:141], v[178:179] op_sel_hi:[1,0]
	v_pk_mul_f32 v[142:143], v[142:143], v[178:179] op_sel_hi:[1,0]
	v_pk_mul_f32 v[144:145], v[144:145], v[178:179] op_sel_hi:[1,0]
	v_pk_mul_f32 v[146:147], v[146:147], v[178:179] op_sel_hi:[1,0]
	v_pk_mul_f32 v[148:149], v[148:149], v[178:179] op_sel_hi:[1,0]
	v_pk_mul_f32 v[150:151], v[150:151], v[178:179] op_sel_hi:[1,0]
	v_pk_mul_f32 v[152:153], v[152:153], v[178:179] op_sel_hi:[1,0]
	s_nop 1
	v_mfma_f32_16x16x32_f16 v[138:141], v[216:219], v[130:133], v[138:141]
	v_mfma_f32_16x16x32_f16 v[142:145], v[224:227], v[130:133], v[142:145]
	v_mfma_f32_16x16x32_f16 v[146:149], v[232:235], v[130:133], v[146:149]
	v_mfma_f32_16x16x32_f16 v[150:153], v[240:243], v[130:133], v[150:153]
	v_mfma_f32_16x16x32_f16 v[138:141], v[220:223], v[134:137], v[138:141]
	v_mfma_f32_16x16x32_f16 v[142:145], v[228:231], v[134:137], v[142:145]
	v_mfma_f32_16x16x32_f16 v[146:149], v[236:239], v[134:137], v[146:149]
	v_mfma_f32_16x16x32_f16 v[150:153], v[244:247], v[134:137], v[150:153]
.Lat0_kb1_end:
	s_waitcnt vmcnt(0)
	ds_write_b128 v158, v[50:53] offset:36864
	ds_write_b128 v158, v[54:57] offset:38016
	ds_write_b128 v158, v[58:61] offset:46080
	ds_write_b128 v158, v[62:65] offset:47232
	s_waitcnt lgkmcnt(0)
	s_barrier
	s_cmp_eq_u32 s4, 1
	s_cbranch_scc0 .Lat0_kb2_end
; DI f4v mfma16(h8v a, h8v b, f4v c) { return __builtin_amdgcn_mfma_f32_16x16x32_f16(a, b, c, 0, 0, 0); }
; DI void mm64(const h16* A, const h16* B, f4v (&acc)[4], int w, int lane) {
;   const int r = lane & 15, q = lane >> 4;
; #pragma unroll
;   for (int s = 0; s < 2; ++s) {
;     h8v a = *(const h8v*)&A[(16 * w + r) * LDH + 32 * s + 8 * q];
; #pragma unroll
;     for (int nt = 0; nt < 4; ++nt) {
;       h8v b = *(const h8v*)&B[(16 * nt + r) * LDH + 32 * s + 8 * q];
;       acc[nt] = mfma16(a, b, acc[nt]);
;     }
;   }
; }
; template <int NKB>
; DI void attn_unit(const Params& p, int l, int mode, int grp, int head, int r0, int dil, int i0, int sub_len, int W, h16* lds) {
;     ...
;     __syncthreads();
;     img_store_nat(Ki, lrow, seg, pk0, pk1);
;     img_store_T(Vt, lrow, seg, pv0, pv1);
;     __syncthreads();
;     if (kb + 1 < NKB) ATT_PREFETCH(kb + 1);
;     f4v S[4];
; #pragma unroll
;     for (int i = 0; i < 4; ++i) S[i] = (f4v){0.f, 0.f, 0.f, 0.f};
;     mm64(Qi, Ki, S, w, lane);
;     float mx[4], al[4], rsum[4];
;     bool vm[4][4];
; #pragma unroll
;     for (int rg = 0; rg < 4; ++rg) {
;       const int row = 16 * w + 4 * q + rg;
;       float m_ = -1e30f;
; #pragma unroll
;       for (int nt = 0; nt < 4; ++nt) {
;         const int key = 16 * nt + r;
;         const int delta = row - key + W - 64 * kb;
;         const bool ok = inr && (delta >= -W) && (delta <= W);
;         vm[nt][rg] = ok;
;         float s = S[nt][rg] * 0.125f;
;         S[nt][rg] = s;
;         if (ok) m_ = fmaxf(m_, s);
;       }
;       mx[rg] = grp16_max(m_);
;     }
; #pragma unroll
;     for (int rg = 0; rg < 4; ++rg) {
;       const float mn = fmaxf(mrow[rg], mx[rg]);
;       al[rg] = __expf(mrow[rg] - mn);
;       mrow[rg] = mn;
;       float rs_ = 0.f;
; #pragma unroll
;       for (int nt = 0; nt < 4; ++nt) {
;         float pv = vm[nt][rg] ? __expf(S[nt][rg] - mn) : 0.f;
;         rs_ += pv;
;         Pi[(16 * w + 4 * q + rg) * LDH + 16 * nt + r] = (h16)pv;
;       }
;       rsum[rg] = grp16_sum(rs_);
;       lsum[rg] = lsum[rg] * al[rg] + rsum[rg];
;     }
; #pragma unroll
;     for (int et = 0; et < 4; ++et)
; #pragma unroll
;       for (int rg = 0; rg < 4; ++rg) O[et][rg] *= al[rg];
;     __syncthreads();
;     mm64(Pi, Vt, O, w, lane);
;   }
	ds_read_b128 v[18:21], v8 offset:36864
	ds_read_b128 v[22:25], v8 offset:36928
	ds_read_b128 v[26:29], v8 offset:39168
	ds_read_b128 v[30:33], v8 offset:39232
	ds_read_b128 v[34:37], v8 offset:41472
	ds_read_b128 v[38:41], v8 offset:41536
	ds_read_b128 v[42:45], v8 offset:43776
	ds_read_b128 v[46:49], v8 offset:43840
	ds_read_b64_tr_b16 v[216:217], v159 offset:36864
	ds_read_b64_tr_b16 v[218:219], v159 offset:39168
	ds_read_b64_tr_b16 v[220:221], v159 offset:41472
	ds_read_b64_tr_b16 v[222:223], v159 offset:43776
	ds_read_b64_tr_b16 v[224:225], v159 offset:36896
	ds_read_b64_tr_b16 v[226:227], v159 offset:39200
	ds_read_b64_tr_b16 v[228:229], v159 offset:41504
	ds_read_b64_tr_b16 v[230:231], v159 offset:43808
	ds_read_b64_tr_b16 v[232:233], v159 offset:36928
	ds_read_b64_tr_b16 v[234:235], v159 offset:39232
	ds_read_b64_tr_b16 v[236:237], v159 offset:41536
	ds_read_b64_tr_b16 v[238:239], v159 offset:43840
	ds_read_b64_tr_b16 v[240:241], v159 offset:36960
	ds_read_b64_tr_b16 v[242:243], v159 offset:39264
	ds_read_b64_tr_b16 v[244:245], v159 offset:41568
	ds_read_b64_tr_b16 v[246:247], v159 offset:43872
	s_waitcnt lgkmcnt(15)
	v_mfma_f32_16x16x32_f16 v[114:117], v[18:21], v[10:13], 0
	v_mfma_f32_16x16x32_f16 v[118:121], v[26:29], v[10:13], 0
	v_mfma_f32_16x16x32_f16 v[122:125], v[34:37], v[10:13], 0
	v_mfma_f32_16x16x32_f16 v[126:129], v[42:45], v[10:13], 0
	v_mfma_f32_16x16x32_f16 v[114:117], v[22:25], v[14:17], v[114:117]
	v_mfma_f32_16x16x32_f16 v[118:121], v[30:33], v[14:17], v[118:121]
	v_mfma_f32_16x16x32_f16 v[122:125], v[38:41], v[14:17], v[122:125]
	v_mfma_f32_16x16x32_f16 v[126:129], v[46:49], v[14:17], v[126:129]
	s_nop 7
	v_mul_f32_e32 v114, 0x3e000000, v114
	v_mul_f32_e32 v115, 0x3e000000, v115
	v_mul_f32_e32 v116, 0x3e000000, v116
	v_mul_f32_e32 v117, 0x3e000000, v117
	v_mul_f32_e32 v118, 0x3e000000, v118
	v_mul_f32_e32 v119, 0x3e000000, v119
	v_mul_f32_e32 v120, 0x3e000000, v120
	v_mul_f32_e32 v121, 0x3e000000, v121
	v_mul_f32_e32 v122, 0x3e000000, v122
	v_mul_f32_e32 v123, 0x3e000000, v123
	v_mul_f32_e32 v124, 0x3e000000, v124
	v_mul_f32_e32 v125, 0x3e000000, v125
	v_mul_f32_e32 v126, 0x3e000000, v126
	v_mul_f32_e32 v127, 0x3e000000, v127
	v_mul_f32_e32 v128, 0x3e000000, v128
	v_mul_f32_e32 v129, 0x3e000000, v129
	v_mov_b32_e32 v200, 0xf149f2ca
	v_cmp_ge_i32_e32 vcc, 0, v160
	v_cndmask_b32_e32 v114, v200, v114, vcc
	v_cmp_ge_i32_e32 vcc, -1, v160
	v_cndmask_b32_e32 v115, v200, v115, vcc
	v_cmp_ge_i32_e32 vcc, -2, v160
	v_cndmask_b32_e32 v116, v200, v116, vcc
	v_cmp_ge_i32_e32 vcc, -3, v160
	v_cndmask_b32_e32 v117, v200, v117, vcc
	v_cmp_ge_i32_e32 vcc, -16, v160
	v_cndmask_b32_e32 v118, v200, v118, vcc
	v_cmp_ge_i32_e32 vcc, -17, v160
	v_cndmask_b32_e32 v119, v200, v119, vcc
	v_cmp_ge_i32_e32 vcc, -18, v160
	v_cndmask_b32_e32 v120, v200, v120, vcc
	v_cmp_ge_i32_e32 vcc, -19, v160
	v_cndmask_b32_e32 v121, v200, v121, vcc
	v_cmp_ge_i32_e32 vcc, -32, v160
	v_cndmask_b32_e32 v122, v200, v122, vcc
	v_cmp_ge_i32_e32 vcc, -33, v160
	v_cndmask_b32_e32 v123, v200, v123, vcc
	v_cmp_ge_i32_e32 vcc, -34, v160
	v_cndmask_b32_e32 v124, v200, v124, vcc
	v_cmp_ge_i32_e32 vcc, -35, v160
	v_cndmask_b32_e32 v125, v200, v125, vcc
	v_cmp_ge_i32_e32 vcc, -48, v160
	v_cndmask_b32_e32 v126, v200, v126, vcc
	v_cmp_ge_i32_e32 vcc, -49, v160
	v_cndmask_b32_e32 v127, v200, v127, vcc
	v_cmp_ge_i32_e32 vcc, -50, v160
	v_cndmask_b32_e32 v128, v200, v128, vcc
	v_cmp_ge_i32_e32 vcc, -51, v160
	v_cndmask_b32_e32 v129, v200, v129, vcc
	v_max3_f32 v179, v114, v115, v116
	v_max3_f32 v179, v179, v117, v118
	v_max3_f32 v179, v179, v119, v120
	v_max3_f32 v179, v179, v121, v122
	v_max3_f32 v179, v179, v123, v124
	v_max3_f32 v179, v179, v125, v126
	v_max3_f32 v179, v179, v127, v128
	v_max_f32_e32 v179, v179, v129
	ds_bpermute_b32 v201, v174, v179
	s_waitcnt lgkmcnt(0)
	v_max_f32_e32 v179, v179, v201
	v_mov_b32_e32 v201, v179
	s_nop 1
	v_permlane32_swap_b32 v201, v179
	s_nop 1
	v_max3_f32 v179, v179, v201, v176
	v_sub_f32_e32 v178, v176, v179
	v_mul_f32_e32 v178, 0x3fb8aa3b, v178
	v_exp_f32_e32 v178, v178
	v_mov_b32_e32 v176, v179
	v_mul_f32_e32 v202, 0xbfb8aa3b, v179
	v_mov_b32_e32 v203, 0x3fb8aa3b
	v_fma_f32 v114, v114, v203, v202
	v_fma_f32 v115, v115, v203, v202
	v_fma_f32 v116, v116, v203, v202
	v_fma_f32 v117, v117, v203, v202
	v_fma_f32 v118, v118, v203, v202
	v_fma_f32 v119, v119, v203, v202
	v_fma_f32 v120, v120, v203, v202
	v_fma_f32 v121, v121, v203, v202
	v_fma_f32 v122, v122, v203, v202
	v_fma_f32 v123, v123, v203, v202
	v_fma_f32 v124, v124, v203, v202
	v_fma_f32 v125, v125, v203, v202
	v_fma_f32 v126, v126, v203, v202
	v_fma_f32 v127, v127, v203, v202
	v_fma_f32 v128, v128, v203, v202
	v_fma_f32 v129, v129, v203, v202
	v_exp_f32_e32 v114, v114
	v_exp_f32_e32 v115, v115
	v_exp_f32_e32 v116, v116
	v_exp_f32_e32 v117, v117
	v_exp_f32_e32 v118, v118
	v_exp_f32_e32 v119, v119
	v_exp_f32_e32 v120, v120
	v_exp_f32_e32 v121, v121
	v_exp_f32_e32 v122, v122
	v_exp_f32_e32 v123, v123
	v_exp_f32_e32 v124, v124
	v_exp_f32_e32 v125, v125
	v_exp_f32_e32 v126, v126
	v_exp_f32_e32 v127, v127
	v_exp_f32_e32 v128, v128
	v_exp_f32_e32 v129, v129
	s_nop 0
	v_fma_f32 v177, v177, v178, v114
	v_add_f32_e32 v177, v177, v115
	v_add_f32_e32 v177, v177, v116
	v_add_f32_e32 v177, v177, v117
	v_add_f32_e32 v177, v177, v118
	v_add_f32_e32 v177, v177, v119
	v_add_f32_e32 v177, v177, v120
	v_add_f32_e32 v177, v177, v121
	v_add_f32_e32 v177, v177, v122
	v_add_f32_e32 v177, v177, v123
	v_add_f32_e32 v177, v177, v124
	v_add_f32_e32 v177, v177, v125
	v_add_f32_e32 v177, v177, v126
	v_add_f32_e32 v177, v177, v127
	v_add_f32_e32 v177, v177, v128
	v_add_f32_e32 v177, v177, v129
	v_cvt_pk_f16_f32 v130, v114, v115
	v_cvt_pk_f16_f32 v131, v116, v117
	v_cvt_pk_f16_f32 v132, v118, v119
	v_cvt_pk_f16_f32 v133, v120, v121
	v_cvt_pk_f16_f32 v134, v122, v123
	v_cvt_pk_f16_f32 v135, v124, v125
	v_cvt_pk_f16_f32 v136, v126, v127
	v_cvt_pk_f16_f32 v137, v128, v129
	v_pk_mul_f32 v[138:139], v[138:139], v[178:179] op_sel_hi:[1,0]
	v_pk_mul_f32 v[140:141], v[140:141], v[178:179] op_sel_hi:[1,0]
	v_pk_mul_f32 v[142:143], v[142:143], v[178:179] op_sel_hi:[1,0]
	v_pk_mul_f32 v[144:145], v[144:145], v[178:179] op_sel_hi:[1,0]
	v_pk_mul_f32 v[146:147], v[146:147], v[178:179] op_sel_hi:[1,0]
	v_pk_mul_f32 v[148:149], v[148:149], v[178:179] op_sel_hi:[1,0]
	v_pk_mul_f32 v[150:151], v[150:151], v[178:179] op_sel_hi:[1,0]
	v_pk_mul_f32 v[152:153], v[152:153], v[178:179] op_sel_hi:[1,0]
	s_nop 1
	v_mfma_f32_16x16x32_f16 v[138:141], v[216:219], v[130:133], v[138:141]
	v_mfma_f32_16x16x32_f16 v[142:145], v[224:227], v[130:133], v[142:145]
	v_mfma_f32_16x16x32_f16 v[146:149], v[232:235], v[130:133], v[146:149]
	v_mfma_f32_16x16x32_f16 v[150:153], v[240:243], v[130:133], v[150:153]
	v_mfma_f32_16x16x32_f16 v[138:141], v[220:223], v[134:137], v[138:141]
	v_mfma_f32_16x16x32_f16 v[142:145], v[228:231], v[134:137], v[142:145]
	v_mfma_f32_16x16x32_f16 v[146:149], v[236:239], v[134:137], v[146:149]
	v_mfma_f32_16x16x32_f16 v[150:153], v[244:247], v[134:137], v[150:153]

; DI int otid() { int t = threadIdx.x & 255; asm volatile("" : "+v"(t)); return t; }
; template <int NKB>
; DI void attn_unit(const Params& p, int l, int mode, int grp, int head, int r0, int dil, int i0, int sub_len, int W, h16* lds) {
;   unsigned char* ws = p.ws;
;   const h16* P = (const h16*)(ws + OFF_PS);
;   h16* Qi = lds; h16* Ki = lds + 64 * LDH; h16* Vt = lds + 128 * LDH; h16* Pi = lds + 192 * LDH;
;   const int tid = otid(), lane = tid & 63, w = tid >> 6, r = lane & 15, q = lane >> 4;
;   const int lrow = tid >> 2, seg = tid & 3;
;   int qcol, kcol, vcol;
;   if (mode == 0) { qcol = 1024 + grp * 256 + head * 64; kcol = 1792 + grp * 256 + head * 64; vcol = 2560 + grp * 256 + head * 64; }
;   else { qcol = 4352 + head * 64; kcol = 4864 + (head >> 2) * 64; vcol = 4992 + (head >> 2) * 64; }
;   __syncthreads();
;   {
;     const size_t pos = (size_t)r0 + (size_t)dil * (i0 + lrow);
;     const h16* g = P + pos * NSM + qcol + 16 * seg;
;     img_store_nat(Qi, lrow, seg, *(const u4v*)g, *(const u4v*)(g + 8));
;   }
;   float mrow[4], lsum[4];
;   f4v O[4];
;   float m_init = -1e30f, l_init = 0.f;
;   if (mode == 1) { m_init = p.d_sink[l * 8 + head]; l_init = 1.f; }
; #pragma unroll
;   for (int i = 0; i < 4; ++i) { mrow[i] = m_init; lsum[i] = l_init; O[i] = (f4v){0.f, 0.f, 0.f, 0.f}; }
;   u4v pk0, pk1, pv0, pv1;
;     ...
;   ATT_PREFETCH(0);
;   for (int kb = 0; kb < NKB; ++kb) {
;     const int j0 = i0 - W + 64 * kb;
;     const bool inr = (j0 >= 0) && (j0 < sub_len);
;     __syncthreads();
;     img_store_nat(Ki, lrow, seg, pk0, pk1);
;     img_store_T(Vt, lrow, seg, pv0, pv1);
;     __syncthreads();
;     if (kb + 1 < NKB) ATT_PREFETCH(kb + 1);
; DI void phase_m2(const Params& p, int l, int bid, int nb, h16* lds) {
;     ...
;     if ((v -= 136) < 2048) { attn_unit<5>(p, l, 1, 0, v & 7, 0, 1, (v >> 3) * 64, SEQ, 128, lds); continue; }
.LBB0_909:
.LBB0_910:
	s_andn2_saveexec_b64 s[34:35], s[34:35]
	s_cbranch_execz .LBB0_914
	v_readfirstlane_b32 s36, v1
	v_readfirstlane_b32 s58, v182
	s_lshr_b32 s58, s58, 6
	s_sub_u32 s51, s36, 0xa8
	s_and_b32 s56, s51, 15
	s_sub_u32 s56, s56, 8
	s_and_b32 s56, s56, 15
	s_lshr_b32 s56, s56, 1
	s_lshr_b32 s57, s51, 4
	s_lshl_b32 s57, s57, 1
	s_and_b32 s59, s51, 1
	s_or_b32 s57, s57, s59
	s_lshl_b32 s56, s56, 8
	s_add_u32 s36, s56, s57
	s_and_b32 s37, s36, 7
	s_lshr_b32 s38, s36, 3
	s_lshl_b32 s38, s38, 6
	s_mov_b32 s40, 0
	s_movk_i32 s39, 0x2800
	s_mov_b32 s60, 1
	s_movk_i32 s41, 0x4000
	s_lshr_b32 s51, s37, 2
	s_lshl_b32 s51, s51, 7
	s_lshl_b32 s56, s37, 7
	s_add_u32 s53, s56, 0x2200
	s_add_u32 s54, s51, 0x2600
	s_add_u32 s55, s51, 0x2700
	v_and_b32_e32 v179, 63, v182
	v_and_b32_e32 v200, 15, v179
	v_lshrrev_b32_e32 v201, 4, v179
	v_lshlrev_b32_e32 v202, 4, v201
	v_mad_u32_u24 v2, v200, s39, v202
	v_add_u32_e32 v203, 16, v200
	v_mad_u32_u24 v3, v203, s39, v202
	v_add_u32_e32 v203, 32, v200
	v_mad_u32_u24 v4, v203, s39, v202
	v_add_u32_e32 v203, 48, v200
	v_mad_u32_u24 v5, v203, s39, v202
	s_lshl_b32 s51, s58, 4
	v_add_u32_e32 v203, s51, v200
	v_mad_u32_u24 v248, v203, s39, v202
	v_lshlrev_b32_e32 v160, 2, v201
	v_sub_u32_e32 v160, v160, v203
	v_mul_u32_u24_e32 v249, 0xa00, v203
	v_lshl_add_u32 v249, v201, 3, v249
	v_lshrrev_b32_e32 v203, 3, v179
	s_lshl_b32 s51, s58, 4
	v_add_u32_e32 v203, s51, v203
	v_and_b32_e32 v202, 7, v179
	v_lshlrev_b32_e32 v202, 4, v202
	v_mad_u32_u24 v6, v203, s39, v202
	v_add_u32_e32 v200, 8, v203
	v_mad_u32_u24 v7, v200, s39, v202
	s_movk_i32 s57, 0x90
	v_mad_u32_u24 v158, v203, s57, v183
	v_add_u32_e32 v158, v158, v202
	v_and_b32_e32 v200, 15, v179
	v_mad_u32_u24 v8, v200, s57, v183
	v_lshl_add_u32 v8, v201, 4, v8
	v_lshrrev_b32_e32 v203, 2, v179
	v_mad_u32_u24 v159, v203, s57, v183
	v_and_b32_e32 v203, 3, v179
	v_lshl_add_u32 v159, v203, 3, v159
	v_add_u32_e32 v159, 0x2400, v159
	v_xor_b32_e32 v174, 16, v179
	v_lshlrev_b32_e32 v174, 2, v174
	v_xor_b32_e32 v175, 32, v179
	v_lshlrev_b32_e32 v175, 2, v175
	s_mul_i32 s51, s60, s38
	s_add_u32 s51, s51, s40
	s_mul_i32 s56, s51, 0x2800
	s_add_u32 s56, s56, s53
	s_add_u32 s42, s0, s56
	s_addc_u32 s43, s1, 0
	global_load_dwordx4 v[10:13], v248, s[42:43]
	global_load_dwordx4 v[14:17], v248, s[42:43] offset:64
	v_readlane_b32 s48, v252, 7
	v_readlane_b32 s49, v252, 8
	s_mul_i32 s56, s38, 0xa00
	s_lshl_b32 s57, s37, 7
	s_add_u32 s56, s56, s57
	s_add_u32 s56, s56, 0x11a80600
	s_nop 2
	s_add_u32 s48, s48, s56
	s_addc_u32 s49, s49, 0
	v_readlane_b32 s18, v252, 27
	v_readlane_b32 s19, v252, 28
	s_or_b32 s56, s92, s37
	s_lshl_b32 s56, s56, 2
	s_nop 3
	s_add_u32 s18, s18, s56
	s_addc_u32 s19, s19, 0
	s_load_dword s56, s[18:19], 0x0
	v_cmp_gt_u32_e32 vcc, 16, v179
	v_cndmask_b32_e64 v177, 0, 1.0, vcc
	s_waitcnt lgkmcnt(0)
	v_mov_b32_e32 v176, s56
	v_mov_b32_e32 v138, 0
	v_mov_b32_e32 v139, 0
	v_mov_b32_e32 v140, 0
	v_mov_b32_e32 v141, 0
	v_mov_b32_e32 v142, 0
	v_mov_b32_e32 v143, 0
	v_mov_b32_e32 v144, 0
	v_mov_b32_e32 v145, 0
	v_mov_b32_e32 v146, 0
	v_mov_b32_e32 v147, 0
	v_mov_b32_e32 v148, 0
	v_mov_b32_e32 v149, 0
	v_mov_b32_e32 v150, 0
	v_mov_b32_e32 v151, 0
	v_mov_b32_e32 v152, 0
	v_mov_b32_e32 v153, 0
	s_sub_u32 s50, s38, 128
	s_cmp_ge_i32 s50, 0
	s_cselect_b32 s56, 1, 0
	s_cmp_lt_i32 s50, s41
	s_cselect_b32 s57, 1, 0
	s_and_b32 s2, s56, s57
	s_cmp_eq_u32 s2, 1
	s_cselect_b32 s50, s50, s38
	s_mul_i32 s50, s50, s60
	s_add_u32 s50, s50, s40
	s_mul_i32 s50, s50, 0x2800
	s_add_u32 s56, s50, s54
	s_add_u32 s44, s0, s56
	s_addc_u32 s45, s1, 0
	s_add_u32 s56, s50, s55
	s_add_u32 s46, s0, s56
	s_addc_u32 s47, s1, 0
	global_load_dwordx4 v[50:53], v6, s[44:45]
	global_load_dwordx4 v[54:57], v7, s[44:45]
	global_load_dwordx4 v[58:61], v6, s[46:47]
	global_load_dwordx4 v[62:65], v7, s[46:47]
	s_sub_u32 s50, s38, 64
	s_cmp_ge_i32 s50, 0
	s_cselect_b32 s56, 1, 0
	s_cmp_lt_i32 s50, s41
	s_cselect_b32 s57, 1, 0
	s_and_b32 s3, s56, s57
	s_cmp_eq_u32 s3, 1
	s_cselect_b32 s50, s50, s38
	s_mul_i32 s50, s50, s60
	s_add_u32 s50, s50, s40
	s_mul_i32 s50, s50, 0x2800
	s_add_u32 s56, s50, s54
	s_add_u32 s44, s0, s56
	s_addc_u32 s45, s1, 0
	s_add_u32 s56, s50, s55
	s_add_u32 s46, s0, s56
	s_addc_u32 s47, s1, 0
	global_load_dwordx4 v[66:69], v6, s[44:45]
	global_load_dwordx4 v[70:73], v7, s[44:45]
	global_load_dwordx4 v[74:77], v6, s[46:47]
	global_load_dwordx4 v[78:81], v7, s[46:47]
	s_waitcnt vmcnt(4)
	ds_write_b128 v158, v[50:53] offset:0
	ds_write_b128 v158, v[54:57] offset:1152
	ds_write_b128 v158, v[58:61] offset:9216
	ds_write_b128 v158, v[62:65] offset:10368
	s_waitcnt lgkmcnt(0)
	s_barrier
	s_add_u32 s50, s38, 0
	s_cmp_ge_i32 s50, 0
	s_cselect_b32 s56, 1, 0
	s_cmp_lt_i32 s50, s41
	s_cselect_b32 s57, 1, 0
	s_and_b32 s4, s56, s57
	s_cmp_eq_u32 s4, 1
	s_cselect_b32 s50, s50, s38
	s_mul_i32 s50, s50, s60
	s_add_u32 s50, s50, s40
	s_mul_i32 s50, s50, 0x2800
	s_add_u32 s56, s50, s54
	s_add_u32 s44, s0, s56
	s_addc_u32 s45, s1, 0
	s_add_u32 s56, s50, s55
	s_add_u32 s46, s0, s56
	s_addc_u32 s47, s1, 0
	global_load_dwordx4 v[50:53], v6, s[44:45]
	global_load_dwordx4 v[54:57], v7, s[44:45]
	global_load_dwordx4 v[58:61], v6, s[46:47]
	global_load_dwordx4 v[62:65], v7, s[46:47]
	s_cmp_eq_u32 s2, 1
	s_cbranch_scc0 .Lat1_kb0_end
; DI f4v mfma16(h8v a, h8v b, f4v c) { return __builtin_amdgcn_mfma_f32_16x16x32_f16(a, b, c, 0, 0, 0); }
; DI void mm64(const h16* A, const h16* B, f4v (&acc)[4], int w, int lane) {
;   const int r = lane & 15, q = lane >> 4;
; #pragma unroll
;   for (int s = 0; s < 2; ++s) {
;     h8v a = *(const h8v*)&A[(16 * w + r) * LDH + 32 * s + 8 * q];
; #pragma unroll
;     for (int nt = 0; nt < 4; ++nt) {
;       h8v b = *(const h8v*)&B[(16 * nt + r) * LDH + 32 * s + 8 * q];
;       acc[nt] = mfma16(a, b, acc[nt]);
;     }
;   }
; }
; template <int NKB>
; DI void attn_unit(const Params& p, int l, int mode, int grp, int head, int r0, int dil, int i0, int sub_len, int W, h16* lds) {
;     ...
;     __syncthreads();
;     img_store_nat(Ki, lrow, seg, pk0, pk1);
;     img_store_T(Vt, lrow, seg, pv0, pv1);
;     __syncthreads();
;     if (kb + 1 < NKB) ATT_PREFETCH(kb + 1);
;     f4v S[4];
; #pragma unroll
;     for (int i = 0; i < 4; ++i) S[i] = (f4v){0.f, 0.f, 0.f, 0.f};
;     mm64(Qi, Ki, S, w, lane);
;     float mx[4], al[4], rsum[4];
;     bool vm[4][4];
; #pragma unroll
;     for (int rg = 0; rg < 4; ++rg) {
;       const int row = 16 * w + 4 * q + rg;
;       float m_ = -1e30f;
; #pragma unroll
;       for (int nt = 0; nt < 4; ++nt) {
;         const int key = 16 * nt + r;
;         const int delta = row - key + W - 64 * kb;
;         const bool ok = inr && (delta >= -W) && (delta <= W);
;         vm[nt][rg] = ok;
;         float s = S[nt][rg] * 0.125f;
;         S[nt][rg] = s;
;         if (ok) m_ = fmaxf(m_, s);
;       }
;       mx[rg] = grp16_max(m_);
;     }
; #pragma unroll
;     for (int rg = 0; rg < 4; ++rg) {
;       const float mn = fmaxf(mrow[rg], mx[rg]);
;       al[rg] = __expf(mrow[rg] - mn);
;       mrow[rg] = mn;
;       float rs_ = 0.f;
; #pragma unroll
;       for (int nt = 0; nt < 4; ++nt) {
;         float pv = vm[nt][rg] ? __expf(S[nt][rg] - mn) : 0.f;
;         rs_ += pv;
;         Pi[(16 * w + 4 * q + rg) * LDH + 16 * nt + r] = (h16)pv;
;       }
;       rsum[rg] = grp16_sum(rs_);
;       lsum[rg] = lsum[rg] * al[rg] + rsum[rg];
;     }
; #pragma unroll
;     for (int et = 0; et < 4; ++et)
; #pragma unroll
;       for (int rg = 0; rg < 4; ++rg) O[et][rg] *= al[rg];
;     __syncthreads();
;     mm64(Pi, Vt, O, w, lane);
;   }
	ds_read_b128 v[18:21], v8 offset:0
	ds_read_b128 v[22:25], v8 offset:64
	ds_read_b128 v[26:29], v8 offset:2304
	ds_read_b128 v[30:33], v8 offset:2368
	ds_read_b128 v[34:37], v8 offset:4608
	ds_read_b128 v[38:41], v8 offset:4672
	ds_read_b128 v[42:45], v8 offset:6912
	ds_read_b128 v[46:49], v8 offset:6976
	ds_read_b64_tr_b16 v[216:217], v159
	ds_read_b64_tr_b16 v[218:219], v159 offset:2304
	ds_read_b64_tr_b16 v[220:221], v159 offset:4608
	ds_read_b64_tr_b16 v[222:223], v159 offset:6912
	ds_read_b64_tr_b16 v[224:225], v159 offset:32
	ds_read_b64_tr_b16 v[226:227], v159 offset:2336
	ds_read_b64_tr_b16 v[228:229], v159 offset:4640
	ds_read_b64_tr_b16 v[230:231], v159 offset:6944
	ds_read_b64_tr_b16 v[232:233], v159 offset:64
	ds_read_b64_tr_b16 v[234:235], v159 offset:2368
	ds_read_b64_tr_b16 v[236:237], v159 offset:4672
	ds_read_b64_tr_b16 v[238:239], v159 offset:6976
	ds_read_b64_tr_b16 v[240:241], v159 offset:96
	ds_read_b64_tr_b16 v[242:243], v159 offset:2400
	ds_read_b64_tr_b16 v[244:245], v159 offset:4704
	ds_read_b64_tr_b16 v[246:247], v159 offset:7008
	s_waitcnt lgkmcnt(15)
	v_mfma_f32_16x16x32_f16 v[114:117], v[18:21], v[10:13], 0
	v_mfma_f32_16x16x32_f16 v[118:121], v[26:29], v[10:13], 0
	v_mfma_f32_16x16x32_f16 v[122:125], v[34:37], v[10:13], 0
	v_mfma_f32_16x16x32_f16 v[126:129], v[42:45], v[10:13], 0
	v_mfma_f32_16x16x32_f16 v[114:117], v[22:25], v[14:17], v[114:117]
	v_mfma_f32_16x16x32_f16 v[118:121], v[30:33], v[14:17], v[118:121]
	v_mfma_f32_16x16x32_f16 v[122:125], v[38:41], v[14:17], v[122:125]
	v_mfma_f32_16x16x32_f16 v[126:129], v[46:49], v[14:17], v[126:129]
	s_nop 7
	v_mul_f32_e32 v114, 0x3e000000, v114
	v_mul_f32_e32 v115, 0x3e000000, v115
	v_mul_f32_e32 v116, 0x3e000000, v116
	v_mul_f32_e32 v117, 0x3e000000, v117
	v_mul_f32_e32 v118, 0x3e000000, v118
	v_mul_f32_e32 v119, 0x3e000000, v119
	v_mul_f32_e32 v120, 0x3e000000, v120
	v_mul_f32_e32 v121, 0x3e000000, v121
	v_mul_f32_e32 v122, 0x3e000000, v122
	v_mul_f32_e32 v123, 0x3e000000, v123
	v_mul_f32_e32 v124, 0x3e000000, v124
	v_mul_f32_e32 v125, 0x3e000000, v125
	v_mul_f32_e32 v126, 0x3e000000, v126
	v_mul_f32_e32 v127, 0x3e000000, v127
	v_mul_f32_e32 v128, 0x3e000000, v128
	v_mul_f32_e32 v129, 0x3e000000, v129
	v_mov_b32_e32 v200, 0xf149f2ca
	v_cmp_le_i32_e32 vcc, 0, v160
	v_cndmask_b32_e32 v114, v200, v114, vcc
	v_cmp_le_i32_e32 vcc, -1, v160
	v_cndmask_b32_e32 v115, v200, v115, vcc
	v_cmp_le_i32_e32 vcc, -2, v160
	v_cndmask_b32_e32 v116, v200, v116, vcc
	v_cmp_le_i32_e32 vcc, -3, v160
	v_cndmask_b32_e32 v117, v200, v117, vcc
	v_cmp_le_i32_e32 vcc, -16, v160
	v_cndmask_b32_e32 v118, v200, v118, vcc
	v_cmp_le_i32_e32 vcc, -17, v160
	v_cndmask_b32_e32 v119, v200, v119, vcc
	v_cmp_le_i32_e32 vcc, -18, v160
	v_cndmask_b32_e32 v120, v200, v120, vcc
	v_cmp_le_i32_e32 vcc, -19, v160
	v_cndmask_b32_e32 v121, v200, v121, vcc
	v_cmp_le_i32_e32 vcc, -32, v160
	v_cndmask_b32_e32 v122, v200, v122, vcc
	v_cmp_le_i32_e32 vcc, -33, v160
	v_cndmask_b32_e32 v123, v200, v123, vcc
	v_cmp_le_i32_e32 vcc, -34, v160
	v_cndmask_b32_e32 v124, v200, v124, vcc
	v_cmp_le_i32_e32 vcc, -35, v160
	v_cndmask_b32_e32 v125, v200, v125, vcc
	v_cmp_le_i32_e32 vcc, -48, v160
	v_cndmask_b32_e32 v126, v200, v126, vcc
	v_cmp_le_i32_e32 vcc, -49, v160
	v_cndmask_b32_e32 v127, v200, v127, vcc
	v_cmp_le_i32_e32 vcc, -50, v160
	v_cndmask_b32_e32 v128, v200, v128, vcc
	v_cmp_le_i32_e32 vcc, -51, v160
	v_cndmask_b32_e32 v129, v200, v129, vcc
	v_max3_f32 v179, v114, v115, v116
	v_max3_f32 v179, v179, v117, v118
	v_max3_f32 v179, v179, v119, v120
	v_max3_f32 v179, v179, v121, v122
	v_max3_f32 v179, v179, v123, v124
	v_max3_f32 v179, v179, v125, v126
	v_max3_f32 v179, v179, v127, v128
	v_max_f32_e32 v179, v179, v129
	ds_bpermute_b32 v201, v174, v179
	s_waitcnt lgkmcnt(0)
	v_max_f32_e32 v179, v179, v201
	v_mov_b32_e32 v201, v179
	s_nop 1
	v_permlane32_swap_b32 v201, v179
	s_nop 1
	v_max3_f32 v179, v179, v201, v176
	v_sub_f32_e32 v178, v176, v179
	v_mul_f32_e32 v178, 0x3fb8aa3b, v178
	v_exp_f32_e32 v178, v178
	v_mov_b32_e32 v176, v179
	v_mul_f32_e32 v202, 0xbfb8aa3b, v179
	v_mov_b32_e32 v203, 0x3fb8aa3b
	v_fma_f32 v114, v114, v203, v202
	v_fma_f32 v115, v115, v203, v202
	v_fma_f32 v116, v116, v203, v202
	v_fma_f32 v117, v117, v203, v202
	v_fma_f32 v118, v118, v203, v202
	v_fma_f32 v119, v119, v203, v202
	v_fma_f32 v120, v120, v203, v202
	v_fma_f32 v121, v121, v203, v202
	v_fma_f32 v122, v122, v203, v202
	v_fma_f32 v123, v123, v203, v202
	v_fma_f32 v124, v124, v203, v202
	v_fma_f32 v125, v125, v203, v202
	v_fma_f32 v126, v126, v203, v202
	v_fma_f32 v127, v127, v203, v202
	v_fma_f32 v128, v128, v203, v202
	v_fma_f32 v129, v129, v203, v202
	v_exp_f32_e32 v114, v114
	v_exp_f32_e32 v115, v115
	v_exp_f32_e32 v116, v116
	v_exp_f32_e32 v117, v117
	v_exp_f32_e32 v118, v118
	v_exp_f32_e32 v119, v119
	v_exp_f32_e32 v120, v120
	v_exp_f32_e32 v121, v121
	v_exp_f32_e32 v122, v122
	v_exp_f32_e32 v123, v123
	v_exp_f32_e32 v124, v124
	v_exp_f32_e32 v125, v125
	v_exp_f32_e32 v126, v126
	v_exp_f32_e32 v127, v127
	v_exp_f32_e32 v128, v128
	v_exp_f32_e32 v129, v129
	s_nop 0
	v_fma_f32 v177, v177, v178, v114
	v_add_f32_e32 v177, v177, v115
	v_add_f32_e32 v177, v177, v116
	v_add_f32_e32 v177, v177, v117
	v_add_f32_e32 v177, v177, v118
	v_add_f32_e32 v177, v177, v119
	v_add_f32_e32 v177, v177, v120
	v_add_f32_e32 v177, v177, v121
	v_add_f32_e32 v177, v177, v122
	v_add_f32_e32 v177, v177, v123
	v_add_f32_e32 v177, v177, v124
	v_add_f32_e32 v177, v177, v125
	v_add_f32_e32 v177, v177, v126
	v_add_f32_e32 v177, v177, v127
	v_add_f32_e32 v177, v177, v128
	v_add_f32_e32 v177, v177, v129
	v_cvt_pk_f16_f32 v130, v114, v115
	v_cvt_pk_f16_f32 v131, v116, v117
	v_cvt_pk_f16_f32 v132, v118, v119
	v_cvt_pk_f16_f32 v133, v120, v121
	v_cvt_pk_f16_f32 v134, v122, v123
	v_cvt_pk_f16_f32 v135, v124, v125
	v_cvt_pk_f16_f32 v136, v126, v127
	v_cvt_pk_f16_f32 v137, v128, v129
	v_pk_mul_f32 v[138:139], v[138:139], v[178:179] op_sel_hi:[1,0]
	v_pk_mul_f32 v[140:141], v[140:141], v[178:179] op_sel_hi:[1,0]
	v_pk_mul_f32 v[142:143], v[142:143], v[178:179] op_sel_hi:[1,0]
	v_pk_mul_f32 v[144:145], v[144:145], v[178:179] op_sel_hi:[1,0]
	v_pk_mul_f32 v[146:147], v[146:147], v[178:179] op_sel_hi:[1,0]
	v_pk_mul_f32 v[148:149], v[148:149], v[178:179] op_sel_hi:[1,0]
	v_pk_mul_f32 v[150:151], v[150:151], v[178:179] op_sel_hi:[1,0]
	v_pk_mul_f32 v[152:153], v[152:153], v[178:179] op_sel_hi:[1,0]
	s_nop 1
	v_mfma_f32_16x16x32_f16 v[138:141], v[216:219], v[130:133], v[138:141]
	v_mfma_f32_16x16x32_f16 v[142:145], v[224:227], v[130:133], v[142:145]
	v_mfma_f32_16x16x32_f16 v[146:149], v[232:235], v[130:133], v[146:149]
	v_mfma_f32_16x16x32_f16 v[150:153], v[240:243], v[130:133], v[150:153]
	v_mfma_f32_16x16x32_f16 v[138:141], v[220:223], v[134:137], v[138:141]
	v_mfma_f32_16x16x32_f16 v[142:145], v[228:231], v[134:137], v[142:145]
	v_mfma_f32_16x16x32_f16 v[146:149], v[236:239], v[134:137], v[146:149]
	v_mfma_f32_16x16x32_f16 v[150:153], v[244:247], v[134:137], v[150:153]
; DI f4v mfma16(h8v a, h8v b, f4v c) { return __builtin_amdgcn_mfma_f32_16x16x32_f16(a, b, c, 0, 0, 0); }
; DI void mm64(const h16* A, const h16* B, f4v (&acc)[4], int w, int lane) {
;   const int r = lane & 15, q = lane >> 4;
; #pragma unroll
;   for (int s = 0; s < 2; ++s) {
;     h8v a = *(const h8v*)&A[(16 * w + r) * LDH + 32 * s + 8 * q];
; #pragma unroll
;     for (int nt = 0; nt < 4; ++nt) {
;       h8v b = *(const h8v*)&B[(16 * nt + r) * LDH + 32 * s + 8 * q];
;       acc[nt] = mfma16(a, b, acc[nt]);
;     }
;   }
; }
; template <int NKB>
; DI void attn_unit(const Params& p, int l, int mode, int grp, int head, int r0, int dil, int i0, int sub_len, int W, h16* lds) {
;     ...
;     __syncthreads();
;     img_store_nat(Ki, lrow, seg, pk0, pk1);
;     img_store_T(Vt, lrow, seg, pv0, pv1);
;     __syncthreads();
;     if (kb + 1 < NKB) ATT_PREFETCH(kb + 1);
;     f4v S[4];
; #pragma unroll
;     for (int i = 0; i < 4; ++i) S[i] = (f4v){0.f, 0.f, 0.f, 0.f};
;     mm64(Qi, Ki, S, w, lane);
;     float mx[4], al[4], rsum[4];
;     bool vm[4][4];
; #pragma unroll
;     for (int rg = 0; rg < 4; ++rg) {
;       const int row = 16 * w + 4 * q + rg;
;       float m_ = -1e30f;
; #pragma unroll
;       for (int nt = 0; nt < 4; ++nt) {
;         const int key = 16 * nt + r;
;         const int delta = row - key + W - 64 * kb;
;         const bool ok = inr && (delta >= -W) && (delta <= W);
;         vm[nt][rg] = ok;
;         float s = S[nt][rg] * 0.125f;
;         S[nt][rg] = s;
;         if (ok) m_ = fmaxf(m_, s);
;       }
;       mx[rg] = grp16_max(m_);
;     }
; #pragma unroll
;     for (int rg = 0; rg < 4; ++rg) {
;       const float mn = fmaxf(mrow[rg], mx[rg]);
;       al[rg] = __expf(mrow[rg] - mn);
;       mrow[rg] = mn;
;       float rs_ = 0.f;
; #pragma unroll
;       for (int nt = 0; nt < 4; ++nt) {
;         float pv = vm[nt][rg] ? __expf(S[nt][rg] - mn) : 0.f;
;         rs_ += pv;
;         Pi[(16 * w + 4 * q + rg) * LDH + 16 * nt + r] = (h16)pv;
;       }
;       rsum[rg] = grp16_sum(rs_);
;       lsum[rg] = lsum[rg] * al[rg] + rsum[rg];
;     }
; #pragma unroll
;     for (int et = 0; et < 4; ++et)
; #pragma unroll
;       for (int rg = 0; rg < 4; ++rg) O[et][rg] *= al[rg];
;     __syncthreads();
;     mm64(Pi, Vt, O, w, lane);
;   }
.Lat1_kb0_end:
	s_waitcnt vmcnt(4)
	ds_write_b128 v158, v[66:69] offset:18432
	ds_write_b128 v158, v[70:73] offset:19584
	ds_write_b128 v158, v[74:77] offset:27648
	ds_write_b128 v158, v[78:81] offset:28800
	s_waitcnt lgkmcnt(0)
	s_barrier
	s_add_u32 s50, s38, 64
	s_cmp_ge_i32 s50, 0
	s_cselect_b32 s56, 1, 0
	s_cmp_lt_i32 s50, s41
	s_cselect_b32 s57, 1, 0
	s_and_b32 s5, s56, s57
	s_cmp_eq_u32 s5, 1
	s_cselect_b32 s50, s50, s38
	s_mul_i32 s50, s50, s60
	s_add_u32 s50, s50, s40
	s_mul_i32 s50, s50, 0x2800
	s_add_u32 s56, s50, s54
	s_add_u32 s44, s0, s56
	s_addc_u32 s45, s1, 0
	s_add_u32 s56, s50, s55
	s_add_u32 s46, s0, s56
	s_addc_u32 s47, s1, 0
	global_load_dwordx4 v[66:69], v6, s[44:45]
	global_load_dwordx4 v[70:73], v7, s[44:45]
	global_load_dwordx4 v[74:77], v6, s[46:47]
	global_load_dwordx4 v[78:81], v7, s[46:47]
	s_cmp_eq_u32 s3, 1
	s_cbranch_scc0 .Lat1_kb1_end
	ds_read_b128 v[18:21], v8 offset:18432
	ds_read_b128 v[22:25], v8 offset:18496
	ds_read_b128 v[26:29], v8 offset:20736
	ds_read_b128 v[30:33], v8 offset:20800
	ds_read_b128 v[34:37], v8 offset:23040
	ds_read_b128 v[38:41], v8 offset:23104
	ds_read_b128 v[42:45], v8 offset:25344
	ds_read_b128 v[46:49], v8 offset:25408
	ds_read_b64_tr_b16 v[216:217], v159 offset:18432
	ds_read_b64_tr_b16 v[218:219], v159 offset:20736
	ds_read_b64_tr_b16 v[220:221], v159 offset:23040
	ds_read_b64_tr_b16 v[222:223], v159 offset:25344
	ds_read_b64_tr_b16 v[224:225], v159 offset:18464
	ds_read_b64_tr_b16 v[226:227], v159 offset:20768
	ds_read_b64_tr_b16 v[228:229], v159 offset:23072
	ds_read_b64_tr_b16 v[230:231], v159 offset:25376
	ds_read_b64_tr_b16 v[232:233], v159 offset:18496
	ds_read_b64_tr_b16 v[234:235], v159 offset:20800
	ds_read_b64_tr_b16 v[236:237], v159 offset:23104
	ds_read_b64_tr_b16 v[238:239], v159 offset:25408
	ds_read_b64_tr_b16 v[240:241], v159 offset:18528
	ds_read_b64_tr_b16 v[242:243], v159 offset:20832
	ds_read_b64_tr_b16 v[244:245], v159 offset:23136
	ds_read_b64_tr_b16 v[246:247], v159 offset:25440
	s_waitcnt lgkmcnt(15)
	v_mfma_f32_16x16x32_f16 v[114:117], v[18:21], v[10:13], 0
	v_mfma_f32_16x16x32_f16 v[118:121], v[26:29], v[10:13], 0
	v_mfma_f32_16x16x32_f16 v[122:125], v[34:37], v[10:13], 0
	v_mfma_f32_16x16x32_f16 v[126:129], v[42:45], v[10:13], 0
	v_mfma_f32_16x16x32_f16 v[114:117], v[22:25], v[14:17], v[114:117]
	v_mfma_f32_16x16x32_f16 v[118:121], v[30:33], v[14:17], v[118:121]
	v_mfma_f32_16x16x32_f16 v[122:125], v[38:41], v[14:17], v[122:125]
	v_mfma_f32_16x16x32_f16 v[126:129], v[46:49], v[14:17], v[126:129]
	s_nop 7
	v_mul_f32_e32 v114, 0x3e000000, v114
	v_mul_f32_e32 v115, 0x3e000000, v115
	v_mul_f32_e32 v116, 0x3e000000, v116
	v_mul_f32_e32 v117, 0x3e000000, v117
	v_mul_f32_e32 v118, 0x3e000000, v118
	v_mul_f32_e32 v119, 0x3e000000, v119
	v_mul_f32_e32 v120, 0x3e000000, v120
	v_mul_f32_e32 v121, 0x3e000000, v121
	v_mul_f32_e32 v122, 0x3e000000, v122
	v_mul_f32_e32 v123, 0x3e000000, v123
	v_mul_f32_e32 v124, 0x3e000000, v124
	v_mul_f32_e32 v125, 0x3e000000, v125
	v_mul_f32_e32 v126, 0x3e000000, v126
	v_mul_f32_e32 v127, 0x3e000000, v127
	v_mul_f32_e32 v128, 0x3e000000, v128
	v_mul_f32_e32 v129, 0x3e000000, v129
	v_max3_f32 v179, v114, v115, v116
	v_max3_f32 v179, v179, v117, v118
	v_max3_f32 v179, v179, v119, v120
	v_max3_f32 v179, v179, v121, v122
	v_max3_f32 v179, v179, v123, v124
	v_max3_f32 v179, v179, v125, v126
	v_max3_f32 v179, v179, v127, v128
	v_max_f32_e32 v179, v179, v129
	ds_bpermute_b32 v201, v174, v179
	s_waitcnt lgkmcnt(0)
	v_max_f32_e32 v179, v179, v201
	v_mov_b32_e32 v201, v179
	s_nop 1
	v_permlane32_swap_b32 v201, v179
	s_nop 1
	v_max3_f32 v179, v179, v201, v176
	v_sub_f32_e32 v178, v176, v179
	v_mul_f32_e32 v178, 0x3fb8aa3b, v178
	v_exp_f32_e32 v178, v178
	v_mov_b32_e32 v176, v179
	v_mul_f32_e32 v202, 0xbfb8aa3b, v179
	v_mov_b32_e32 v203, 0x3fb8aa3b
	v_fma_f32 v114, v114, v203, v202
	v_fma_f32 v115, v115, v203, v202
	v_fma_f32 v116, v116, v203, v202
	v_fma_f32 v117, v117, v203, v202
	v_fma_f32 v118, v118, v203, v202
	v_fma_f32 v119, v119, v203, v202
	v_fma_f32 v120, v120, v203, v202
	v_fma_f32 v121, v121, v203, v202
	v_fma_f32 v122, v122, v203, v202
	v_fma_f32 v123, v123, v203, v202
	v_fma_f32 v124, v124, v203, v202
	v_fma_f32 v125, v125, v203, v202
	v_fma_f32 v126, v126, v203, v202
	v_fma_f32 v127, v127, v203, v202
	v_fma_f32 v128, v128, v203, v202
	v_fma_f32 v129, v129, v203, v202
	v_exp_f32_e32 v114, v114
	v_exp_f32_e32 v115, v115
	v_exp_f32_e32 v116, v116
	v_exp_f32_e32 v117, v117
	v_exp_f32_e32 v118, v118
	v_exp_f32_e32 v119, v119
	v_exp_f32_e32 v120, v120
	v_exp_f32_e32 v121, v121
	v_exp_f32_e32 v122, v122
	v_exp_f32_e32 v123, v123
	v_exp_f32_e32 v124, v124
	v_exp_f32_e32 v125, v125
	v_exp_f32_e32 v126, v126
	v_exp_f32_e32 v127, v127
	v_exp_f32_e32 v128, v128
	v_exp_f32_e32 v129, v129
	s_nop 0
	v_fma_f32 v177, v177, v178, v114
	v_add_f32_e32 v177, v177, v115
	v_add_f32_e32 v177, v177, v116
	v_add_f32_e32 v177, v177, v117
	v_add_f32_e32 v177, v177, v118
	v_add_f32_e32 v177, v177, v119
	v_add_f32_e32 v177, v177, v120
	v_add_f32_e32 v177, v177, v121
	v_add_f32_e32 v177, v177, v122
	v_add_f32_e32 v177, v177, v123
	v_add_f32_e32 v177, v177, v124
	v_add_f32_e32 v177, v177, v125
	v_add_f32_e32 v177, v177, v126
	v_add_f32_e32 v177, v177, v127
	v_add_f32_e32 v177, v177, v128
	v_add_f32_e32 v177, v177, v129
	v_cvt_pk_f16_f32 v130, v114, v115
	v_cvt_pk_f16_f32 v131, v116, v117
	v_cvt_pk_f16_f32 v132, v118, v119
	v_cvt_pk_f16_f32 v133, v120, v121
	v_cvt_pk_f16_f32 v134, v122, v123
	v_cvt_pk_f16_f32 v135, v124, v125
	v_cvt_pk_f16_f32 v136, v126, v127
	v_cvt_pk_f16_f32 v137, v128, v129
	v_pk_mul_f32 v[138:139], v[138:139], v[178:179] op_sel_hi:[1,0]
	v_pk_mul_f32 v[140:141], v[140:141], v[178:179] op_sel_hi:[1,0]
	v_pk_mul_f32 v[142:143], v[142:143], v[178:179] op_sel_hi:[1,0]
	v_pk_mul_f32 v[144:145], v[144:145], v[178:179] op_sel_hi:[1,0]
	v_pk_mul_f32 v[146:147], v[146:147], v[178:179] op_sel_hi:[1,0]
	v_pk_mul_f32 v[148:149], v[148:149], v[178:179] op_sel_hi:[1,0]
	v_pk_mul_f32 v[150:151], v[150:151], v[178:179] op_sel_hi:[1,0]
	v_pk_mul_f32 v[152:153], v[152:153], v[178:179] op_sel_hi:[1,0]
	s_nop 1
	v_mfma_f32_16x16x32_f16 v[138:141], v[216:219], v[130:133], v[138:141]
	v_mfma_f32_16x16x32_f16 v[142:145], v[224:227], v[130:133], v[142:145]
	v_mfma_f32_16x16x32_f16 v[146:149], v[232:235], v[130:133], v[146:149]
	v_mfma_f32_16x16x32_f16 v[150:153], v[240:243], v[130:133], v[150:153]
	v_mfma_f32_16x16x32_f16 v[138:141], v[220:223], v[134:137], v[138:141]
	v_mfma_f32_16x16x32_f16 v[142:145], v[228:231], v[134:137], v[142:145]
	v_mfma_f32_16x16x32_f16 v[146:149], v[236:239], v[134:137], v[146:149]
	v_mfma_f32_16x16x32_f16 v[150:153], v[244:247], v[134:137], v[150:153]
; DI f4v mfma16(h8v a, h8v b, f4v c) { return __builtin_amdgcn_mfma_f32_16x16x32_f16(a, b, c, 0, 0, 0); }
; DI void mm64(const h16* A, const h16* B, f4v (&acc)[4], int w, int lane) {
;   const int r = lane & 15, q = lane >> 4;
; #pragma unroll
;   for (int s = 0; s < 2; ++s) {
;     h8v a = *(const h8v*)&A[(16 * w + r) * LDH + 32 * s + 8 * q];
; #pragma unroll
;     for (int nt = 0; nt < 4; ++nt) {
;       h8v b = *(const h8v*)&B[(16 * nt + r) * LDH + 32 * s + 8 * q];
;       acc[nt] = mfma16(a, b, acc[nt]);
;     }
;   }
; }
; template <int NKB>
; DI void attn_unit(const Params& p, int l, int mode, int grp, int head, int r0, int dil, int i0, int sub_len, int W, h16* lds) {
;     ...
;     __syncthreads();
;     img_store_nat(Ki, lrow, seg, pk0, pk1);
;     img_store_T(Vt, lrow, seg, pv0, pv1);
;     __syncthreads();
;     if (kb + 1 < NKB) ATT_PREFETCH(kb + 1);
;     f4v S[4];
; #pragma unroll
;     for (int i = 0; i < 4; ++i) S[i] = (f4v){0.f, 0.f, 0.f, 0.f};
;     mm64(Qi, Ki, S, w, lane);
;     float mx[4], al[4], rsum[4];
;     bool vm[4][4];
; #pragma unroll
;     for (int rg = 0; rg < 4; ++rg) {
;       const int row = 16 * w + 4 * q + rg;
;       float m_ = -1e30f;
; #pragma unroll
;       for (int nt = 0; nt < 4; ++nt) {
;         const int key = 16 * nt + r;
;         const int delta = row - key + W - 64 * kb;
;         const bool ok = inr && (delta >= -W) && (delta <= W);
;         vm[nt][rg] = ok;
;         float s = S[nt][rg] * 0.125f;
;         S[nt][rg] = s;
;         if (ok) m_ = fmaxf(m_, s);
;       }
;       mx[rg] = grp16_max(m_);
;     }
; #pragma unroll
;     for (int rg = 0; rg < 4; ++rg) {
;       const float mn = fmaxf(mrow[rg], mx[rg]);
;       al[rg] = __expf(mrow[rg] - mn);
;       mrow[rg] = mn;
;       float rs_ = 0.f;
; #pragma unroll
;       for (int nt = 0; nt < 4; ++nt) {
;         float pv = vm[nt][rg] ? __expf(S[nt][rg] - mn) : 0.f;
;         rs_ += pv;
;         Pi[(16 * w + 4 * q + rg) * LDH + 16 * nt + r] = (h16)pv;
;       }
;       rsum[rg] = grp16_sum(rs_);
;       lsum[rg] = lsum[rg] * al[rg] + rsum[rg];
;     }
; #pragma unroll
;     for (int et = 0; et < 4; ++et)
; #pragma unroll
;       for (int rg = 0; rg < 4; ++rg) O[et][rg] *= al[rg];
;     __syncthreads();
;     mm64(Pi, Vt, O, w, lane);
;   }
.Lat1_kb1_end:
	s_waitcnt vmcnt(4)
	ds_write_b128 v158, v[50:53] offset:36864
	ds_write_b128 v158, v[54:57] offset:38016
	ds_write_b128 v158, v[58:61] offset:46080
	ds_write_b128 v158, v[62:65] offset:47232
	s_waitcnt lgkmcnt(0)
	s_barrier
	s_add_u32 s50, s38, 128
	s_cmp_ge_i32 s50, 0
	s_cselect_b32 s56, 1, 0
	s_cmp_lt_i32 s50, s41
	s_cselect_b32 s57, 1, 0
	s_and_b32 s6, s56, s57
	s_cmp_eq_u32 s6, 1
	s_cselect_b32 s50, s50, s38
	s_mul_i32 s50, s50, s60
	s_add_u32 s50, s50, s40
	s_mul_i32 s50, s50, 0x2800
	s_add_u32 s56, s50, s54
	s_add_u32 s44, s0, s56
	s_addc_u32 s45, s1, 0
	s_add_u32 s56, s50, s55
	s_add_u32 s46, s0, s56
	s_addc_u32 s47, s1, 0
	global_load_dwordx4 v[50:53], v6, s[44:45]
	global_load_dwordx4 v[54:57], v7, s[44:45]
	global_load_dwordx4 v[58:61], v6, s[46:47]
	global_load_dwordx4 v[62:65], v7, s[46:47]
	s_cmp_eq_u32 s4, 1
	s_cbranch_scc0 .Lat1_kb2_end
	ds_read_b128 v[18:21], v8 offset:36864
	ds_read_b128 v[22:25], v8 offset:36928
	ds_read_b128 v[26:29], v8 offset:39168
	ds_read_b128 v[30:33], v8 offset:39232
	ds_read_b128 v[34:37], v8 offset:41472
	ds_read_b128 v[38:41], v8 offset:41536
	ds_read_b128 v[42:45], v8 offset:43776
	ds_read_b128 v[46:49], v8 offset:43840
	ds_read_b64_tr_b16 v[216:217], v159 offset:36864
	ds_read_b64_tr_b16 v[218:219], v159 offset:39168
	ds_read_b64_tr_b16 v[220:221], v159 offset:41472
	ds_read_b64_tr_b16 v[222:223], v159 offset:43776
	ds_read_b64_tr_b16 v[224:225], v159 offset:36896
	ds_read_b64_tr_b16 v[226:227], v159 offset:39200
	ds_read_b64_tr_b16 v[228:229], v159 offset:41504
	ds_read_b64_tr_b16 v[230:231], v159 offset:43808
	ds_read_b64_tr_b16 v[232:233], v159 offset:36928
	ds_read_b64_tr_b16 v[234:235], v159 offset:39232
	ds_read_b64_tr_b16 v[236:237], v159 offset:41536
	ds_read_b64_tr_b16 v[238:239], v159 offset:43840
	ds_read_b64_tr_b16 v[240:241], v159 offset:36960
	ds_read_b64_tr_b16 v[242:243], v159 offset:39264
	ds_read_b64_tr_b16 v[244:245], v159 offset:41568
	ds_read_b64_tr_b16 v[246:247], v159 offset:43872
	s_waitcnt lgkmcnt(15)
	v_mfma_f32_16x16x32_f16 v[114:117], v[18:21], v[10:13], 0
	v_mfma_f32_16x16x32_f16 v[118:121], v[26:29], v[10:13], 0
	v_mfma_f32_16x16x32_f16 v[122:125], v[34:37], v[10:13], 0
	v_mfma_f32_16x16x32_f16 v[126:129], v[42:45], v[10:13], 0
	v_mfma_f32_16x16x32_f16 v[114:117], v[22:25], v[14:17], v[114:117]
	v_mfma_f32_16x16x32_f16 v[118:121], v[30:33], v[14:17], v[118:121]
	v_mfma_f32_16x16x32_f16 v[122:125], v[38:41], v[14:17], v[122:125]
	v_mfma_f32_16x16x32_f16 v[126:129], v[46:49], v[14:17], v[126:129]
	s_nop 7
	v_mul_f32_e32 v114, 0x3e000000, v114
	v_mul_f32_e32 v115, 0x3e000000, v115
	v_mul_f32_e32 v116, 0x3e000000, v116
	v_mul_f32_e32 v117, 0x3e000000, v117
	v_mul_f32_e32 v118, 0x3e000000, v118
	v_mul_f32_e32 v119, 0x3e000000, v119
	v_mul_f32_e32 v120, 0x3e000000, v120
	v_mul_f32_e32 v121, 0x3e000000, v121
	v_mul_f32_e32 v122, 0x3e000000, v122
	v_mul_f32_e32 v123, 0x3e000000, v123
	v_mul_f32_e32 v124, 0x3e000000, v124
	v_mul_f32_e32 v125, 0x3e000000, v125
	v_mul_f32_e32 v126, 0x3e000000, v126
	v_mul_f32_e32 v127, 0x3e000000, v127
	v_mul_f32_e32 v128, 0x3e000000, v128
	v_mul_f32_e32 v129, 0x3e000000, v129
	v_max3_f32 v179, v114, v115, v116
	v_max3_f32 v179, v179, v117, v118
	v_max3_f32 v179, v179, v119, v120
	v_max3_f32 v179, v179, v121, v122
	v_max3_f32 v179, v179, v123, v124
	v_max3_f32 v179, v179, v125, v126
	v_max3_f32 v179, v179, v127, v128
	v_max_f32_e32 v179, v179, v129
	ds_bpermute_b32 v201, v174, v179
	s_waitcnt lgkmcnt(0)
	v_max_f32_e32 v179, v179, v201
	v_mov_b32_e32 v201, v179
	s_nop 1
	v_permlane32_swap_b32 v201, v179
	s_nop 1
	v_max3_f32 v179, v179, v201, v176
	v_sub_f32_e32 v178, v176, v179
	v_mul_f32_e32 v178, 0x3fb8aa3b, v178
	v_exp_f32_e32 v178, v178
	v_mov_b32_e32 v176, v179
	v_mul_f32_e32 v202, 0xbfb8aa3b, v179
	v_mov_b32_e32 v203, 0x3fb8aa3b
	v_fma_f32 v114, v114, v203, v202
	v_fma_f32 v115, v115, v203, v202
	v_fma_f32 v116, v116, v203, v202
	v_fma_f32 v117, v117, v203, v202
	v_fma_f32 v118, v118, v203, v202
	v_fma_f32 v119, v119, v203, v202
	v_fma_f32 v120, v120, v203, v202
	v_fma_f32 v121, v121, v203, v202
	v_fma_f32 v122, v122, v203, v202
	v_fma_f32 v123, v123, v203, v202
	v_fma_f32 v124, v124, v203, v202
	v_fma_f32 v125, v125, v203, v202
	v_fma_f32 v126, v126, v203, v202
	v_fma_f32 v127, v127, v203, v202
	v_fma_f32 v128, v128, v203, v202
	v_fma_f32 v129, v129, v203, v202
	v_exp_f32_e32 v114, v114
	v_exp_f32_e32 v115, v115
	v_exp_f32_e32 v116, v116
	v_exp_f32_e32 v117, v117
	v_exp_f32_e32 v118, v118
	v_exp_f32_e32 v119, v119
	v_exp_f32_e32 v120, v120
	v_exp_f32_e32 v121, v121
	v_exp_f32_e32 v122, v122
	v_exp_f32_e32 v123, v123
	v_exp_f32_e32 v124, v124
	v_exp_f32_e32 v125, v125
	v_exp_f32_e32 v126, v126
	v_exp_f32_e32 v127, v127
	v_exp_f32_e32 v128, v128
	v_exp_f32_e32 v129, v129
	s_nop 0
	v_fma_f32 v177, v177, v178, v114
	v_add_f32_e32 v177, v177, v115
	v_add_f32_e32 v177, v177, v116
	v_add_f32_e32 v177, v177, v117
	v_add_f32_e32 v177, v177, v118
	v_add_f32_e32 v177, v177, v119
	v_add_f32_e32 v177, v177, v120
	v_add_f32_e32 v177, v177, v121
	v_add_f32_e32 v177, v177, v122
	v_add_f32_e32 v177, v177, v123
	v_add_f32_e32 v177, v177, v124
	v_add_f32_e32 v177, v177, v125
	v_add_f32_e32 v177, v177, v126
	v_add_f32_e32 v177, v177, v127
	v_add_f32_e32 v177, v177, v128
	v_add_f32_e32 v177, v177, v129
	v_cvt_pk_f16_f32 v130, v114, v115
	v_cvt_pk_f16_f32 v131, v116, v117
	v_cvt_pk_f16_f32 v132, v118, v119
	v_cvt_pk_f16_f32 v133, v120, v121
	v_cvt_pk_f16_f32 v134, v122, v123
	v_cvt_pk_f16_f32 v135, v124, v125
	v_cvt_pk_f16_f32 v136, v126, v127
	v_cvt_pk_f16_f32 v137, v128, v129
	v_pk_mul_f32 v[138:139], v[138:139], v[178:179] op_sel_hi:[1,0]
	v_pk_mul_f32 v[140:141], v[140:141], v[178:179] op_sel_hi:[1,0]
	v_pk_mul_f32 v[142:143], v[142:143], v[178:179] op_sel_hi:[1,0]
	v_pk_mul_f32 v[144:145], v[144:145], v[178:179] op_sel_hi:[1,0]
	v_pk_mul_f32 v[146:147], v[146:147], v[178:179] op_sel_hi:[1,0]
	v_pk_mul_f32 v[148:149], v[148:149], v[178:179] op_sel_hi:[1,0]
	v_pk_mul_f32 v[150:151], v[150:151], v[178:179] op_sel_hi:[1,0]
	v_pk_mul_f32 v[152:153], v[152:153], v[178:179] op_sel_hi:[1,0]
	s_nop 1
	v_mfma_f32_16x16x32_f16 v[138:141], v[216:219], v[130:133], v[138:141]
	v_mfma_f32_16x16x32_f16 v[142:145], v[224:227], v[130:133], v[142:145]
	v_mfma_f32_16x16x32_f16 v[146:149], v[232:235], v[130:133], v[146:149]
	v_mfma_f32_16x16x32_f16 v[150:153], v[240:243], v[130:133], v[150:153]
	v_mfma_f32_16x16x32_f16 v[138:141], v[220:223], v[134:137], v[138:141]
	v_mfma_f32_16x16x32_f16 v[142:145], v[228:231], v[134:137], v[142:145]
	v_mfma_f32_16x16x32_f16 v[146:149], v[236:239], v[134:137], v[146:149]
	v_mfma_f32_16x16x32_f16 v[150:153], v[244:247], v[134:137], v[150:153]
; DI f4v mfma16(h8v a, h8v b, f4v c) { return __builtin_amdgcn_mfma_f32_16x16x32_f16(a, b, c, 0, 0, 0); }
; DI void mm64(const h16* A, const h16* B, f4v (&acc)[4], int w, int lane) {
;   const int r = lane & 15, q = lane >> 4;
; #pragma unroll
;   for (int s = 0; s < 2; ++s) {
;     h8v a = *(const h8v*)&A[(16 * w + r) * LDH + 32 * s + 8 * q];
; #pragma unroll
;     for (int nt = 0; nt < 4; ++nt) {
;       h8v b = *(const h8v*)&B[(16 * nt + r) * LDH + 32 * s + 8 * q];
;       acc[nt] = mfma16(a, b, acc[nt]);
;     }
;   }
; }
; template <int NKB>
; DI void attn_unit(const Params& p, int l, int mode, int grp, int head, int r0, int dil, int i0, int sub_len, int W, h16* lds) {
;     ...
;     __syncthreads();
;     img_store_nat(Ki, lrow, seg, pk0, pk1);
;     img_store_T(Vt, lrow, seg, pv0, pv1);
;     __syncthreads();
;     if (kb + 1 < NKB) ATT_PREFETCH(kb + 1);
;     f4v S[4];
; #pragma unroll
;     for (int i = 0; i < 4; ++i) S[i] = (f4v){0.f, 0.f, 0.f, 0.f};
;     mm64(Qi, Ki, S, w, lane);
;     float mx[4], al[4], rsum[4];
;     bool vm[4][4];
; #pragma unroll
;     for (int rg = 0; rg < 4; ++rg) {
;       const int row = 16 * w + 4 * q + rg;
;       float m_ = -1e30f;
; #pragma unroll
;       for (int nt = 0; nt < 4; ++nt) {
;         const int key = 16 * nt + r;
;         const int delta = row - key + W - 64 * kb;
;         const bool ok = inr && (delta >= -W) && (delta <= W);
;         vm[nt][rg] = ok;
;         float s = S[nt][rg] * 0.125f;
;         S[nt][rg] = s;
;         if (ok) m_ = fmaxf(m_, s);
;       }
;       mx[rg] = grp16_max(m_);
;     }
; #pragma unroll
;     for (int rg = 0; rg < 4; ++rg) {
;       const float mn = fmaxf(mrow[rg], mx[rg]);
;       al[rg] = __expf(mrow[rg] - mn);
;       mrow[rg] = mn;
;       float rs_ = 0.f;
; #pragma unroll
;       for (int nt = 0; nt < 4; ++nt) {
;         float pv = vm[nt][rg] ? __expf(S[nt][rg] - mn) : 0.f;
;         rs_ += pv;
;         Pi[(16 * w + 4 * q + rg) * LDH + 16 * nt + r] = (h16)pv;
;       }
;       rsum[rg] = grp16_sum(rs_);
;       lsum[rg] = lsum[rg] * al[rg] + rsum[rg];
;     }
; #pragma unroll
;     for (int et = 0; et < 4; ++et)
; #pragma unroll
;       for (int rg = 0; rg < 4; ++rg) O[et][rg] *= al[rg];
;     __syncthreads();
;     mm64(Pi, Vt, O, w, lane);
;   }
.Lat1_kb2_end:
	s_waitcnt vmcnt(4)
	ds_write_b128 v158, v[66:69] offset:0
	ds_write_b128 v158, v[70:73] offset:1152
	ds_write_b128 v158, v[74:77] offset:9216
	ds_write_b128 v158, v[78:81] offset:10368
	s_waitcnt lgkmcnt(0)
	s_barrier
	s_cmp_eq_u32 s5, 1
	s_cbranch_scc0 .Lat1_kb3_end
	ds_read_b128 v[18:21], v8 offset:0
	ds_read_b128 v[22:25], v8 offset:64
	ds_read_b128 v[26:29], v8 offset:2304
	ds_read_b128 v[30:33], v8 offset:2368
	ds_read_b128 v[34:37], v8 offset:4608
	ds_read_b128 v[38:41], v8 offset:4672
	ds_read_b128 v[42:45], v8 offset:6912
	ds_read_b128 v[46:49], v8 offset:6976
	ds_read_b64_tr_b16 v[216:217], v159
	ds_read_b64_tr_b16 v[218:219], v159 offset:2304
	ds_read_b64_tr_b16 v[220:221], v159 offset:4608
	ds_read_b64_tr_b16 v[222:223], v159 offset:6912
	ds_read_b64_tr_b16 v[224:225], v159 offset:32
	ds_read_b64_tr_b16 v[226:227], v159 offset:2336
	ds_read_b64_tr_b16 v[228:229], v159 offset:4640
	ds_read_b64_tr_b16 v[230:231], v159 offset:6944
	ds_read_b64_tr_b16 v[232:233], v159 offset:64
	ds_read_b64_tr_b16 v[234:235], v159 offset:2368
	ds_read_b64_tr_b16 v[236:237], v159 offset:4672
	ds_read_b64_tr_b16 v[238:239], v159 offset:6976
	ds_read_b64_tr_b16 v[240:241], v159 offset:96
	ds_read_b64_tr_b16 v[242:243], v159 offset:2400
	ds_read_b64_tr_b16 v[244:245], v159 offset:4704
	ds_read_b64_tr_b16 v[246:247], v159 offset:7008
	s_waitcnt lgkmcnt(15)
	v_mfma_f32_16x16x32_f16 v[114:117], v[18:21], v[10:13], 0
	v_mfma_f32_16x16x32_f16 v[118:121], v[26:29], v[10:13], 0
	v_mfma_f32_16x16x32_f16 v[122:125], v[34:37], v[10:13], 0
	v_mfma_f32_16x16x32_f16 v[126:129], v[42:45], v[10:13], 0
	v_mfma_f32_16x16x32_f16 v[114:117], v[22:25], v[14:17], v[114:117]
	v_mfma_f32_16x16x32_f16 v[118:121], v[30:33], v[14:17], v[118:121]
	v_mfma_f32_16x16x32_f16 v[122:125], v[38:41], v[14:17], v[122:125]
	v_mfma_f32_16x16x32_f16 v[126:129], v[46:49], v[14:17], v[126:129]
	s_nop 7
	v_mul_f32_e32 v114, 0x3e000000, v114
	v_mul_f32_e32 v115, 0x3e000000, v115
	v_mul_f32_e32 v116, 0x3e000000, v116
	v_mul_f32_e32 v117, 0x3e000000, v117
	v_mul_f32_e32 v118, 0x3e000000, v118
	v_mul_f32_e32 v119, 0x3e000000, v119
	v_mul_f32_e32 v120, 0x3e000000, v120
	v_mul_f32_e32 v121, 0x3e000000, v121
	v_mul_f32_e32 v122, 0x3e000000, v122
	v_mul_f32_e32 v123, 0x3e000000, v123
	v_mul_f32_e32 v124, 0x3e000000, v124
	v_mul_f32_e32 v125, 0x3e000000, v125
	v_mul_f32_e32 v126, 0x3e000000, v126
	v_mul_f32_e32 v127, 0x3e000000, v127
	v_mul_f32_e32 v128, 0x3e000000, v128
	v_mul_f32_e32 v129, 0x3e000000, v129
	v_max3_f32 v179, v114, v115, v116
	v_max3_f32 v179, v179, v117, v118
	v_max3_f32 v179, v179, v119, v120
	v_max3_f32 v179, v179, v121, v122
	v_max3_f32 v179, v179, v123, v124
	v_max3_f32 v179, v179, v125, v126
	v_max3_f32 v179, v179, v127, v128
	v_max_f32_e32 v179, v179, v129
	ds_bpermute_b32 v201, v174, v179
	s_waitcnt lgkmcnt(0)
	v_max_f32_e32 v179, v179, v201
	v_mov_b32_e32 v201, v179
	s_nop 1
	v_permlane32_swap_b32 v201, v179
	s_nop 1
	v_max3_f32 v179, v179, v201, v176
	v_sub_f32_e32 v178, v176, v179
	v_mul_f32_e32 v178, 0x3fb8aa3b, v178
	v_exp_f32_e32 v178, v178
	v_mov_b32_e32 v176, v179
	v_mul_f32_e32 v202, 0xbfb8aa3b, v179
	v_mov_b32_e32 v203, 0x3fb8aa3b
	v_fma_f32 v114, v114, v203, v202
	v_fma_f32 v115, v115, v203, v202
	v_fma_f32 v116, v116, v203, v202
	v_fma_f32 v117, v117, v203, v202
	v_fma_f32 v118, v118, v203, v202
	v_fma_f32 v119, v119, v203, v202
	v_fma_f32 v120, v120, v203, v202
	v_fma_f32 v121, v121, v203, v202
	v_fma_f32 v122, v122, v203, v202
	v_fma_f32 v123, v123, v203, v202
	v_fma_f32 v124, v124, v203, v202
	v_fma_f32 v125, v125, v203, v202
	v_fma_f32 v126, v126, v203, v202
	v_fma_f32 v127, v127, v203, v202
	v_fma_f32 v128, v128, v203, v202
	v_fma_f32 v129, v129, v203, v202
	v_exp_f32_e32 v114, v114
	v_exp_f32_e32 v115, v115
	v_exp_f32_e32 v116, v116
	v_exp_f32_e32 v117, v117
	v_exp_f32_e32 v118, v118
	v_exp_f32_e32 v119, v119
	v_exp_f32_e32 v120, v120
	v_exp_f32_e32 v121, v121
	v_exp_f32_e32 v122, v122
	v_exp_f32_e32 v123, v123
	v_exp_f32_e32 v124, v124
	v_exp_f32_e32 v125, v125
	v_exp_f32_e32 v126, v126
	v_exp_f32_e32 v127, v127
	v_exp_f32_e32 v128, v128
	v_exp_f32_e32 v129, v129
	s_nop 0
	v_fma_f32 v177, v177, v178, v114
	v_add_f32_e32 v177, v177, v115
	v_add_f32_e32 v177, v177, v116
	v_add_f32_e32 v177, v177, v117
	v_add_f32_e32 v177, v177, v118
	v_add_f32_e32 v177, v177, v119
	v_add_f32_e32 v177, v177, v120
	v_add_f32_e32 v177, v177, v121
	v_add_f32_e32 v177, v177, v122
	v_add_f32_e32 v177, v177, v123
	v_add_f32_e32 v177, v177, v124
	v_add_f32_e32 v177, v177, v125
	v_add_f32_e32 v177, v177, v126
	v_add_f32_e32 v177, v177, v127
	v_add_f32_e32 v177, v177, v128
	v_add_f32_e32 v177, v177, v129
	v_cvt_pk_f16_f32 v130, v114, v115
	v_cvt_pk_f16_f32 v131, v116, v117
	v_cvt_pk_f16_f32 v132, v118, v119
	v_cvt_pk_f16_f32 v133, v120, v121
	v_cvt_pk_f16_f32 v134, v122, v123
	v_cvt_pk_f16_f32 v135, v124, v125
	v_cvt_pk_f16_f32 v136, v126, v127
	v_cvt_pk_f16_f32 v137, v128, v129
	v_pk_mul_f32 v[138:139], v[138:139], v[178:179] op_sel_hi:[1,0]
	v_pk_mul_f32 v[140:141], v[140:141], v[178:179] op_sel_hi:[1,0]
	v_pk_mul_f32 v[142:143], v[142:143], v[178:179] op_sel_hi:[1,0]
	v_pk_mul_f32 v[144:145], v[144:145], v[178:179] op_sel_hi:[1,0]
	v_pk_mul_f32 v[146:147], v[146:147], v[178:179] op_sel_hi:[1,0]
	v_pk_mul_f32 v[148:149], v[148:149], v[178:179] op_sel_hi:[1,0]
	v_pk_mul_f32 v[150:151], v[150:151], v[178:179] op_sel_hi:[1,0]
	v_pk_mul_f32 v[152:153], v[152:153], v[178:179] op_sel_hi:[1,0]
	s_nop 1
	v_mfma_f32_16x16x32_f16 v[138:141], v[216:219], v[130:133], v[138:141]
	v_mfma_f32_16x16x32_f16 v[142:145], v[224:227], v[130:133], v[142:145]
	v_mfma_f32_16x16x32_f16 v[146:149], v[232:235], v[130:133], v[146:149]
	v_mfma_f32_16x16x32_f16 v[150:153], v[240:243], v[130:133], v[150:153]
	v_mfma_f32_16x16x32_f16 v[138:141], v[220:223], v[134:137], v[138:141]
	v_mfma_f32_16x16x32_f16 v[142:145], v[228:231], v[134:137], v[142:145]
	v_mfma_f32_16x16x32_f16 v[146:149], v[236:239], v[134:137], v[146:149]
	v_mfma_f32_16x16x32_f16 v[150:153], v[244:247], v[134:137], v[150:153]
; template <int NKB>
; DI void attn_unit(const Params& p, int l, int mode, int grp, int head, int r0, int dil, int i0, int sub_len, int W, h16* lds) {
;     ...
;     __syncthreads();
;     img_store_nat(Ki, lrow, seg, pk0, pk1);
;     img_store_T(Vt, lrow, seg, pv0, pv1);
;     __syncthreads();
.Lat1_kb3_end:
	s_waitcnt vmcnt(0)
	ds_write_b128 v158, v[50:53] offset:18432
	ds_write_b128 v158, v[54:57] offset:19584
	ds_write_b128 v158, v[58:61] offset:27648
	ds_write_b128 v158, v[62:65] offset:28800
	s_waitcnt lgkmcnt(0)
	s_barrier
	s_cmp_eq_u32 s6, 1
	s_cbranch_scc0 .Lat1_kb4_end
; DI f4v mfma16(h8v a, h8v b, f4v c) { return __builtin_amdgcn_mfma_f32_16x16x32_f16(a, b, c, 0, 0, 0); }
; DI void mm64(const h16* A, const h16* B, f4v (&acc)[4], int w, int lane) {
;   const int r = lane & 15, q = lane >> 4;
; #pragma unroll
;   for (int s = 0; s < 2; ++s) {
;     h8v a = *(const h8v*)&A[(16 * w + r) * LDH + 32 * s + 8 * q];
; #pragma unroll
;     for (int nt = 0; nt < 4; ++nt) {
;       h8v b = *(const h8v*)&B[(16 * nt + r) * LDH + 32 * s + 8 * q];
;       acc[nt] = mfma16(a, b, acc[nt]);
;     }
;   }
; }
; template <int NKB>
; DI void attn_unit(const Params& p, int l, int mode, int grp, int head, int r0, int dil, int i0, int sub_len, int W, h16* lds) {
;     ...
;     __syncthreads();
;     img_store_nat(Ki, lrow, seg, pk0, pk1);
;     img_store_T(Vt, lrow, seg, pv0, pv1);
;     __syncthreads();
;     if (kb + 1 < NKB) ATT_PREFETCH(kb + 1);
;     f4v S[4];
; #pragma unroll
;     for (int i = 0; i < 4; ++i) S[i] = (f4v){0.f, 0.f, 0.f, 0.f};
;     mm64(Qi, Ki, S, w, lane);
;     float mx[4], al[4], rsum[4];
;     bool vm[4][4];
; #pragma unroll
;     for (int rg = 0; rg < 4; ++rg) {
;       const int row = 16 * w + 4 * q + rg;
;       float m_ = -1e30f;
; #pragma unroll
;       for (int nt = 0; nt < 4; ++nt) {
;         const int key = 16 * nt + r;
;         const int delta = row - key + W - 64 * kb;
;         const bool ok = inr && (delta >= -W) && (delta <= W);
;         vm[nt][rg] = ok;
;         float s = S[nt][rg] * 0.125f;
;         S[nt][rg] = s;
;         if (ok) m_ = fmaxf(m_, s);
;       }
;       mx[rg] = grp16_max(m_);
;     }
; #pragma unroll
;     for (int rg = 0; rg < 4; ++rg) {
;       const float mn = fmaxf(mrow[rg], mx[rg]);
;       al[rg] = __expf(mrow[rg] - mn);
;       mrow[rg] = mn;
;       float rs_ = 0.f;
; #pragma unroll
;       for (int nt = 0; nt < 4; ++nt) {
;         float pv = vm[nt][rg] ? __expf(S[nt][rg] - mn) : 0.f;
;         rs_ += pv;
;         Pi[(16 * w + 4 * q + rg) * LDH + 16 * nt + r] = (h16)pv;
;       }
;       rsum[rg] = grp16_sum(rs_);
;       lsum[rg] = lsum[rg] * al[rg] + rsum[rg];
;     }
; #pragma unroll
;     for (int et = 0; et < 4; ++et)
; #pragma unroll
;       for (int rg = 0; rg < 4; ++rg) O[et][rg] *= al[rg];
;     __syncthreads();
;     mm64(Pi, Vt, O, w, lane);
;   }
	ds_read_b128 v[18:21], v8 offset:18432
	ds_read_b128 v[22:25], v8 offset:18496
	ds_read_b128 v[26:29], v8 offset:20736
	ds_read_b128 v[30:33], v8 offset:20800
	ds_read_b128 v[34:37], v8 offset:23040
	ds_read_b128 v[38:41], v8 offset:23104
	ds_read_b128 v[42:45], v8 offset:25344
	ds_read_b128 v[46:49], v8 offset:25408
	ds_read_b64_tr_b16 v[216:217], v159 offset:18432
	ds_read_b64_tr_b16 v[218:219], v159 offset:20736
	ds_read_b64_tr_b16 v[220:221], v159 offset:23040
	ds_read_b64_tr_b16 v[222:223], v159 offset:25344
	ds_read_b64_tr_b16 v[224:225], v159 offset:18464
	ds_read_b64_tr_b16 v[226:227], v159 offset:20768
	ds_read_b64_tr_b16 v[228:229], v159 offset:23072
	ds_read_b64_tr_b16 v[230:231], v159 offset:25376
	ds_read_b64_tr_b16 v[232:233], v159 offset:18496
	ds_read_b64_tr_b16 v[234:235], v159 offset:20800
	ds_read_b64_tr_b16 v[236:237], v159 offset:23104
	ds_read_b64_tr_b16 v[238:239], v159 offset:25408
	ds_read_b64_tr_b16 v[240:241], v159 offset:18528
	ds_read_b64_tr_b16 v[242:243], v159 offset:20832
	ds_read_b64_tr_b16 v[244:245], v159 offset:23136
	ds_read_b64_tr_b16 v[246:247], v159 offset:25440
	s_waitcnt lgkmcnt(15)
	v_mfma_f32_16x16x32_f16 v[114:117], v[18:21], v[10:13], 0
	v_mfma_f32_16x16x32_f16 v[118:121], v[26:29], v[10:13], 0
	v_mfma_f32_16x16x32_f16 v[122:125], v[34:37], v[10:13], 0
	v_mfma_f32_16x16x32_f16 v[126:129], v[42:45], v[10:13], 0
	v_mfma_f32_16x16x32_f16 v[114:117], v[22:25], v[14:17], v[114:117]
	v_mfma_f32_16x16x32_f16 v[118:121], v[30:33], v[14:17], v[118:121]
	v_mfma_f32_16x16x32_f16 v[122:125], v[38:41], v[14:17], v[122:125]
	v_mfma_f32_16x16x32_f16 v[126:129], v[46:49], v[14:17], v[126:129]
	s_nop 7
	v_mul_f32_e32 v114, 0x3e000000, v114
	v_mul_f32_e32 v115, 0x3e000000, v115
	v_mul_f32_e32 v116, 0x3e000000, v116
	v_mul_f32_e32 v117, 0x3e000000, v117
	v_mul_f32_e32 v118, 0x3e000000, v118
	v_mul_f32_e32 v119, 0x3e000000, v119
	v_mul_f32_e32 v120, 0x3e000000, v120
	v_mul_f32_e32 v121, 0x3e000000, v121
	v_mul_f32_e32 v122, 0x3e000000, v122
	v_mul_f32_e32 v123, 0x3e000000, v123
	v_mul_f32_e32 v124, 0x3e000000, v124
	v_mul_f32_e32 v125, 0x3e000000, v125
	v_mul_f32_e32 v126, 0x3e000000, v126
	v_mul_f32_e32 v127, 0x3e000000, v127
	v_mul_f32_e32 v128, 0x3e000000, v128
	v_mul_f32_e32 v129, 0x3e000000, v129
	v_mov_b32_e32 v200, 0xf149f2ca
	v_cmp_ge_i32_e32 vcc, 0, v160
	v_cndmask_b32_e32 v114, v200, v114, vcc
	v_cmp_ge_i32_e32 vcc, -1, v160
	v_cndmask_b32_e32 v115, v200, v115, vcc
	v_cmp_ge_i32_e32 vcc, -2, v160
	v_cndmask_b32_e32 v116, v200, v116, vcc
	v_cmp_ge_i32_e32 vcc, -3, v160
	v_cndmask_b32_e32 v117, v200, v117, vcc
	v_cmp_ge_i32_e32 vcc, -16, v160
	v_cndmask_b32_e32 v118, v200, v118, vcc
	v_cmp_ge_i32_e32 vcc, -17, v160
	v_cndmask_b32_e32 v119, v200, v119, vcc
	v_cmp_ge_i32_e32 vcc, -18, v160
	v_cndmask_b32_e32 v120, v200, v120, vcc
	v_cmp_ge_i32_e32 vcc, -19, v160
	v_cndmask_b32_e32 v121, v200, v121, vcc
	v_cmp_ge_i32_e32 vcc, -32, v160
	v_cndmask_b32_e32 v122, v200, v122, vcc
	v_cmp_ge_i32_e32 vcc, -33, v160
	v_cndmask_b32_e32 v123, v200, v123, vcc
	v_cmp_ge_i32_e32 vcc, -34, v160
	v_cndmask_b32_e32 v124, v200, v124, vcc
	v_cmp_ge_i32_e32 vcc, -35, v160
	v_cndmask_b32_e32 v125, v200, v125, vcc
	v_cmp_ge_i32_e32 vcc, -48, v160
	v_cndmask_b32_e32 v126, v200, v126, vcc
	v_cmp_ge_i32_e32 vcc, -49, v160
	v_cndmask_b32_e32 v127, v200, v127, vcc
	v_cmp_ge_i32_e32 vcc, -50, v160
	v_cndmask_b32_e32 v128, v200, v128, vcc
	v_cmp_ge_i32_e32 vcc, -51, v160
	v_cndmask_b32_e32 v129, v200, v129, vcc
	v_max3_f32 v179, v114, v115, v116
	v_max3_f32 v179, v179, v117, v118
	v_max3_f32 v179, v179, v119, v120
	v_max3_f32 v179, v179, v121, v122
	v_max3_f32 v179, v179, v123, v124
	v_max3_f32 v179, v179, v125, v126
	v_max3_f32 v179, v179, v127, v128
	v_max_f32_e32 v179, v179, v129
	ds_bpermute_b32 v201, v174, v179
	s_waitcnt lgkmcnt(0)
	v_max_f32_e32 v179, v179, v201
	v_mov_b32_e32 v201, v179
	s_nop 1
	v_permlane32_swap_b32 v201, v179
	s_nop 1
	v_max3_f32 v179, v179, v201, v176
	v_sub_f32_e32 v178, v176, v179
	v_mul_f32_e32 v178, 0x3fb8aa3b, v178
	v_exp_f32_e32 v178, v178
	v_mov_b32_e32 v176, v179
	v_mul_f32_e32 v202, 0xbfb8aa3b, v179
	v_mov_b32_e32 v203, 0x3fb8aa3b
	v_fma_f32 v114, v114, v203, v202
	v_fma_f32 v115, v115, v203, v202
	v_fma_f32 v116, v116, v203, v202
	v_fma_f32 v117, v117, v203, v202
	v_fma_f32 v118, v118, v203, v202
	v_fma_f32 v119, v119, v203, v202
	v_fma_f32 v120, v120, v203, v202
	v_fma_f32 v121, v121, v203, v202
	v_fma_f32 v122, v122, v203, v202
	v_fma_f32 v123, v123, v203, v202
	v_fma_f32 v124, v124, v203, v202
	v_fma_f32 v125, v125, v203, v202
	v_fma_f32 v126, v126, v203, v202
	v_fma_f32 v127, v127, v203, v202
	v_fma_f32 v128, v128, v203, v202
	v_fma_f32 v129, v129, v203, v202
	v_exp_f32_e32 v114, v114
	v_exp_f32_e32 v115, v115
	v_exp_f32_e32 v116, v116
	v_exp_f32_e32 v117, v117
	v_exp_f32_e32 v118, v118
	v_exp_f32_e32 v119, v119
	v_exp_f32_e32 v120, v120
	v_exp_f32_e32 v121, v121
	v_exp_f32_e32 v122, v122
	v_exp_f32_e32 v123, v123
	v_exp_f32_e32 v124, v124
	v_exp_f32_e32 v125, v125
	v_exp_f32_e32 v126, v126
	v_exp_f32_e32 v127, v127
	v_exp_f32_e32 v128, v128
	v_exp_f32_e32 v129, v129
	s_nop 0
	v_fma_f32 v177, v177, v178, v114
	v_add_f32_e32 v177, v177, v115
	v_add_f32_e32 v177, v177, v116
	v_add_f32_e32 v177, v177, v117
	v_add_f32_e32 v177, v177, v118
	v_add_f32_e32 v177, v177, v119
	v_add_f32_e32 v177, v177, v120
	v_add_f32_e32 v177, v177, v121
	v_add_f32_e32 v177, v177, v122
	v_add_f32_e32 v177, v177, v123
	v_add_f32_e32 v177, v177, v124
	v_add_f32_e32 v177, v177, v125
	v_add_f32_e32 v177, v177, v126
	v_add_f32_e32 v177, v177, v127
	v_add_f32_e32 v177, v177, v128
	v_add_f32_e32 v177, v177, v129
	v_cvt_pk_f16_f32 v130, v114, v115
	v_cvt_pk_f16_f32 v131, v116, v117
	v_cvt_pk_f16_f32 v132, v118, v119
	v_cvt_pk_f16_f32 v133, v120, v121
	v_cvt_pk_f16_f32 v134, v122, v123
	v_cvt_pk_f16_f32 v135, v124, v125
	v_cvt_pk_f16_f32 v136, v126, v127
	v_cvt_pk_f16_f32 v137, v128, v129
	v_pk_mul_f32 v[138:139], v[138:139], v[178:179] op_sel_hi:[1,0]
	v_pk_mul_f32 v[140:141], v[140:141], v[178:179] op_sel_hi:[1,0]
	v_pk_mul_f32 v[142:143], v[142:143], v[178:179] op_sel_hi:[1,0]
	v_pk_mul_f32 v[144:145], v[144:145], v[178:179] op_sel_hi:[1,0]
	v_pk_mul_f32 v[146:147], v[146:147], v[178:179] op_sel_hi:[1,0]
	v_pk_mul_f32 v[148:149], v[148:149], v[178:179] op_sel_hi:[1,0]
	v_pk_mul_f32 v[150:151], v[150:151], v[178:179] op_sel_hi:[1,0]
	v_pk_mul_f32 v[152:153], v[152:153], v[178:179] op_sel_hi:[1,0]
	s_nop 1
	v_mfma_f32_16x16x32_f16 v[138:141], v[216:219], v[130:133], v[138:141]
	v_mfma_f32_16x16x32_f16 v[142:145], v[224:227], v[130:133], v[142:145]
	v_mfma_f32_16x16x32_f16 v[146:149], v[232:235], v[130:133], v[146:149]
	v_mfma_f32_16x16x32_f16 v[150:153], v[240:243], v[130:133], v[150:153]
	v_mfma_f32_16x16x32_f16 v[138:141], v[220:223], v[134:137], v[138:141]
	v_mfma_f32_16x16x32_f16 v[142:145], v[228:231], v[134:137], v[142:145]
	v_mfma_f32_16x16x32_f16 v[146:149], v[236:239], v[134:137], v[146:149]
	v_mfma_f32_16x16x32_f16 v[150:153], v[244:247], v[134:137], v[150:153]
